# stage-DMA waits per segment with vmcnt(10): five segments of latency slack instead of three
# speedup vs baseline: 1.0009x; 1.0009x over previous
; #define G_STAGE(bufoff, gbase) do { _Pragma("unroll") for (int _i = 0; _i < 2; ++_i) \
;         __builtin_amdgcn_global_load_lds((const unsigned*)((const char*)(gbase) + voff[_i]), (LAS unsigned*)(lds + (bufoff) + ldsw + _i * 8192), 16, 0, 0); } while (0)
; #define G_LDA(dst, b, h) do { _Pragma("unroll") for (int m = 0; m < 4; ++m) _Pragma("unroll") for (int k = 0; k < 2; ++k) dst[m][k] = *(const LAS bf16x8*)(lds + G_SA(b, h) + aoff + m * 2048 + k * 1024); } while (0)
; #define G_LDB(dst, b, h) do { _Pragma("unroll") for (int n = 0; n < 2; ++n) _Pragma("unroll") for (int k = 0; k < 2; ++k) dst[n][k] = *(const LAS bf16x8*)(lds + G_SB(b, h) + boff + n * 2048 + k * 1024); } while (0)
; #define G_MMA(ai, bj, At, Bt) do { __builtin_amdgcn_s_setprio(1); _Pragma("unroll") for (int m = 0; m < 4; ++m) _Pragma("unroll") for (int n = 0; n < 2; ++n) _Pragma("unroll") for (int k = 0; k < 2; ++k) \
;         acc[ai][bj][m][n] = MFMA16(Bt[n][k], At[m][k], acc[ai][bj][m][n]); __builtin_amdgcn_s_setprio(0); } while (0)
; #define G_WAIT_V(n) asm volatile("s_waitcnt vmcnt(" #n ")" ::: "memory")
; #define G_WAIT_L(n) asm volatile("s_waitcnt lgkmcnt(" #n ")" ::: "memory")
; #define G_BAR __builtin_amdgcn_s_barrier()
; #define G_SCHED __builtin_amdgcn_sched_barrier(0)
; template <class Epi>
; __device__ __forceinline__ void gemm_phase(LAS unsigned char* lds, const bf16_t* Ag, const bf16_t* Btg, const int K, const int nM, const int nN, const Epi& E) {
;     ...
;             G_LDB(B0, 0, 0); G_SCHED; G_LDA(At, 0, 0); G_STAGE(G_SA(1, 1), a1 + hstep);
;             G_WAIT_L(8); G_BAR; G_WAIT_L(0); G_MMA(0, 0, At, B0); G_BAR; G_SCHED;
;             G_LDB(B1, 0, 1); G_STAGE(G_SB(0, 0), b2);
;             G_BAR; G_WAIT_L(0); G_MMA(0, 1, At, B1); G_BAR;
;             G_LDA(At, 0, 1); G_STAGE(G_SA(0, 0), a2);
;             G_BAR; G_WAIT_L(0); G_MMA(1, 0, At, B0); G_BAR; G_SCHED;
;             G_STAGE(G_SB(0, 1), b2 + hstep);
;             G_WAIT_V(6); G_BAR; G_MMA(1, 1, At, B1); G_BAR;
.LmainW_78:
	ds_read_b128 v[124:127], v217
	ds_read_b128 v[128:131], v217 offset:1024
	ds_read_b128 v[132:135], v217 offset:2048
	ds_read_b128 v[136:139], v217 offset:3072
	s_add_i32 m0, s58, 0xc000
	ds_read_b128 v[140:143], v186
	ds_read_b128 v[148:151], v186 offset:1024
	ds_read_b128 v[152:155], v186 offset:2048
	ds_read_b128 v[156:159], v186 offset:3072
	ds_read_b128 v[188:191], v186 offset:4096
	ds_read_b128 v[192:195], v186 offset:5120
	ds_read_b128 v[222:225], v186 offset:6144
	global_load_lds_dwordx4 v170, s[50:51]
	s_add_i32 m0, s58, 0xe000
	ds_read_b128 v[226:229], v186 offset:7168
	global_load_lds_dwordx4 v168, s[50:51]
	s_waitcnt vmcnt(10) lgkmcnt(8)
	s_barrier
	s_waitcnt lgkmcnt(0)
	s_waitcnt lgkmcnt(0)
	v_mfma_f32_16x16x32_bf16 v[164:167], v[124:127], v[140:143], v[164:167]
	v_mfma_f32_16x16x32_bf16 v[160:163], v[132:135], v[140:143], v[160:163]
	v_mfma_f32_16x16x32_bf16 v[116:119], v[124:127], v[152:155], v[116:119]
	v_mfma_f32_16x16x32_bf16 v[112:115], v[132:135], v[152:155], v[112:115]
	v_mfma_f32_16x16x32_bf16 v[100:103], v[124:127], v[188:191], v[100:103]
	v_mfma_f32_16x16x32_bf16 v[96:99], v[132:135], v[188:191], v[96:99]
	v_mfma_f32_16x16x32_bf16 v[84:87], v[124:127], v[222:225], v[84:87]
	v_mfma_f32_16x16x32_bf16 v[80:83], v[132:135], v[222:225], v[80:83]
	v_mfma_f32_16x16x32_bf16 v[164:167], v[128:131], v[148:151], v[164:167]
	v_mfma_f32_16x16x32_bf16 v[160:163], v[136:139], v[148:151], v[160:163]
	v_mfma_f32_16x16x32_bf16 v[116:119], v[128:131], v[156:159], v[116:119]
	v_mfma_f32_16x16x32_bf16 v[112:115], v[136:139], v[156:159], v[112:115]
	v_mfma_f32_16x16x32_bf16 v[100:103], v[128:131], v[192:195], v[100:103]
	v_mfma_f32_16x16x32_bf16 v[96:99], v[136:139], v[192:195], v[96:99]
	v_mfma_f32_16x16x32_bf16 v[84:87], v[128:131], v[226:229], v[84:87]
	v_mfma_f32_16x16x32_bf16 v[80:83], v[136:139], v[226:229], v[80:83]
	s_barrier
	ds_read_b128 v[230:233], v217 offset:16384
	ds_read_b128 v[234:237], v217 offset:17408
	s_add_i32 m0, s57, 0x10000
	ds_read_b128 v[238:241], v217 offset:18432
	global_load_lds_dwordx4 v0, s[52:53]
	s_add_i32 m0, s57, 0x12000
	ds_read_b128 v[242:245], v217 offset:19456
	global_load_lds_dwordx4 v2, s[52:53]
	s_waitcnt vmcnt(10)
	s_barrier
	s_waitcnt lgkmcnt(0)
	s_waitcnt lgkmcnt(0)
	v_mfma_f32_16x16x32_bf16 v[144:147], v[230:233], v[140:143], v[144:147]
	v_mfma_f32_16x16x32_bf16 v[120:123], v[238:241], v[140:143], v[120:123]
	v_mfma_f32_16x16x32_bf16 v[108:111], v[230:233], v[152:155], v[108:111]
	v_mfma_f32_16x16x32_bf16 v[104:107], v[238:241], v[152:155], v[104:107]
	v_mfma_f32_16x16x32_bf16 v[92:95], v[230:233], v[188:191], v[92:95]
	v_mfma_f32_16x16x32_bf16 v[88:91], v[238:241], v[188:191], v[88:91]
	v_mfma_f32_16x16x32_bf16 v[76:79], v[230:233], v[222:225], v[76:79]
	v_mfma_f32_16x16x32_bf16 v[72:75], v[238:241], v[222:225], v[72:75]
	v_mfma_f32_16x16x32_bf16 v[144:147], v[234:237], v[148:151], v[144:147]
	v_mfma_f32_16x16x32_bf16 v[120:123], v[242:245], v[148:151], v[120:123]
	v_mfma_f32_16x16x32_bf16 v[108:111], v[234:237], v[156:159], v[108:111]
	v_mfma_f32_16x16x32_bf16 v[104:107], v[242:245], v[156:159], v[104:107]
	v_mfma_f32_16x16x32_bf16 v[92:95], v[234:237], v[192:195], v[92:95]
	v_mfma_f32_16x16x32_bf16 v[88:91], v[242:245], v[192:195], v[88:91]
	v_mfma_f32_16x16x32_bf16 v[76:79], v[234:237], v[226:229], v[76:79]
	v_mfma_f32_16x16x32_bf16 v[72:75], v[242:245], v[226:229], v[72:75]
	s_mov_b32 m0, s58
	s_barrier
	ds_read_b128 v[140:143], v186 offset:16384
	ds_read_b128 v[148:151], v186 offset:17408
	ds_read_b128 v[152:155], v186 offset:18432
	ds_read_b128 v[156:159], v186 offset:19456
	ds_read_b128 v[188:191], v186 offset:20480
	ds_read_b128 v[192:195], v186 offset:21504
	ds_read_b128 v[222:225], v186 offset:22528
	global_load_lds_dwordx4 v0, s[54:55]
	s_mov_b32 m0, s59
	ds_read_b128 v[226:229], v186 offset:23552
	global_load_lds_dwordx4 v2, s[54:55]
	s_barrier
	s_waitcnt lgkmcnt(0)
	s_waitcnt lgkmcnt(0)
	v_mfma_f32_16x16x32_bf16 v[60:63], v[124:127], v[140:143], v[60:63]
	v_mfma_f32_16x16x32_bf16 v[56:59], v[132:135], v[140:143], v[56:59]
	v_mfma_f32_16x16x32_bf16 v[44:47], v[124:127], v[152:155], v[44:47]
	v_mfma_f32_16x16x32_bf16 v[40:43], v[132:135], v[152:155], v[40:43]
	v_mfma_f32_16x16x32_bf16 v[28:31], v[124:127], v[188:191], v[28:31]
	v_mfma_f32_16x16x32_bf16 v[24:27], v[132:135], v[188:191], v[24:27]
	v_mfma_f32_16x16x32_bf16 v[12:15], v[124:127], v[222:225], v[12:15]
	v_mfma_f32_16x16x32_bf16 v[8:11], v[132:135], v[222:225], v[8:11]
	v_mfma_f32_16x16x32_bf16 v[60:63], v[128:131], v[148:151], v[60:63]
	v_mfma_f32_16x16x32_bf16 v[56:59], v[136:139], v[148:151], v[56:59]
	v_mfma_f32_16x16x32_bf16 v[44:47], v[128:131], v[156:159], v[44:47]
	v_mfma_f32_16x16x32_bf16 v[40:43], v[136:139], v[156:159], v[40:43]
	v_mfma_f32_16x16x32_bf16 v[28:31], v[128:131], v[192:195], v[28:31]
	v_mfma_f32_16x16x32_bf16 v[24:27], v[136:139], v[192:195], v[24:27]
	v_mfma_f32_16x16x32_bf16 v[12:15], v[128:131], v[226:229], v[12:15]
	v_mfma_f32_16x16x32_bf16 v[8:11], v[136:139], v[226:229], v[8:11]
	s_barrier
	s_add_i32 m0, s57, 0x14000
	s_add_u32 s74, s52, 0x40000
	s_addc_u32 s75, s53, 0
	global_load_lds_dwordx4 v0, s[74:75]
	s_add_i32 m0, s57, 0x16000
	s_add_u32 s54, s54, 0x40000
	s_addc_u32 s55, s55, 0
	global_load_lds_dwordx4 v2, s[74:75]
	s_waitcnt vmcnt(10)
	s_barrier
; #define G_STAGE(bufoff, gbase) do { _Pragma("unroll") for (int _i = 0; _i < 2; ++_i) \
;         __builtin_amdgcn_global_load_lds((const unsigned*)((const char*)(gbase) + voff[_i]), (LAS unsigned*)(lds + (bufoff) + ldsw + _i * 8192), 16, 0, 0); } while (0)
; #define G_LDA(dst, b, h) do { _Pragma("unroll") for (int m = 0; m < 4; ++m) _Pragma("unroll") for (int k = 0; k < 2; ++k) dst[m][k] = *(const LAS bf16x8*)(lds + G_SA(b, h) + aoff + m * 2048 + k * 1024); } while (0)
; #define G_LDB(dst, b, h) do { _Pragma("unroll") for (int n = 0; n < 2; ++n) _Pragma("unroll") for (int k = 0; k < 2; ++k) dst[n][k] = *(const LAS bf16x8*)(lds + G_SB(b, h) + boff + n * 2048 + k * 1024); } while (0)
; #define G_MMA(ai, bj, At, Bt) do { __builtin_amdgcn_s_setprio(1); _Pragma("unroll") for (int m = 0; m < 4; ++m) _Pragma("unroll") for (int n = 0; n < 2; ++n) _Pragma("unroll") for (int k = 0; k < 2; ++k) \
;         acc[ai][bj][m][n] = MFMA16(Bt[n][k], At[m][k], acc[ai][bj][m][n]); __builtin_amdgcn_s_setprio(0); } while (0)
; #define G_WAIT_V(n) asm volatile("s_waitcnt vmcnt(" #n ")" ::: "memory")
; #define G_WAIT_L(n) asm volatile("s_waitcnt lgkmcnt(" #n ")" ::: "memory")
; #define G_BAR __builtin_amdgcn_s_barrier()
; #define G_SCHED __builtin_amdgcn_sched_barrier(0)
; template <class Epi>
; __device__ __forceinline__ void gemm_phase(LAS unsigned char* lds, const bf16_t* Ag, const bf16_t* Btg, const int K, const int nM, const int nN, const Epi& E) {
;     ...
;         for (int t = 0; t < nt; t += 2) {
;             const bool last = (t == nt - 2);
;             const char* a1 = cA + (size_t)(t + 1) * kstep;
;             const char* a2 = last ? nA : cA + (size_t)(t + 2) * kstep; const char* b2 = last ? nB : cB + (size_t)(t + 2) * kstep;
;             const char* a3 = a2 + kstep; const char* b3 = b2 + kstep;
;     ...
;             G_WAIT_V(6); G_BAR; G_MMA(1, 1, At, B1); G_BAR;
;             G_LDB(B0, 1, 0); G_SCHED; G_LDA(At, 1, 0); G_STAGE(G_SA(0, 1), a2 + hstep);
;             G_WAIT_L(8); G_BAR; G_WAIT_L(0); G_MMA(0, 0, At, B0); G_BAR; G_SCHED;
;             G_LDB(B1, 1, 1); G_STAGE(G_SB(1, 0), b3);
;             G_BAR; G_WAIT_L(0); G_MMA(0, 1, At, B1); G_BAR;
;             G_LDA(At, 1, 1); G_STAGE(G_SA(1, 0), a3);
;             G_BAR; G_WAIT_L(0); G_MMA(1, 0, At, B0); G_BAR; G_SCHED;
;             G_STAGE(G_SB(1, 1), b3 + hstep);
	v_mfma_f32_16x16x32_bf16 v[68:71], v[230:233], v[140:143], v[68:71]
	v_mfma_f32_16x16x32_bf16 v[64:67], v[238:241], v[140:143], v[64:67]
	v_mfma_f32_16x16x32_bf16 v[52:55], v[230:233], v[152:155], v[52:55]
	v_mfma_f32_16x16x32_bf16 v[48:51], v[238:241], v[152:155], v[48:51]
	v_mfma_f32_16x16x32_bf16 v[36:39], v[230:233], v[188:191], v[36:39]
	v_mfma_f32_16x16x32_bf16 v[32:35], v[238:241], v[188:191], v[32:35]
	v_mfma_f32_16x16x32_bf16 v[20:23], v[230:233], v[222:225], v[20:23]
	v_mfma_f32_16x16x32_bf16 v[16:19], v[238:241], v[222:225], v[16:19]
	v_mfma_f32_16x16x32_bf16 v[68:71], v[234:237], v[148:151], v[68:71]
	v_mfma_f32_16x16x32_bf16 v[64:67], v[242:245], v[148:151], v[64:67]
	v_mfma_f32_16x16x32_bf16 v[52:55], v[234:237], v[156:159], v[52:55]
	v_mfma_f32_16x16x32_bf16 v[48:51], v[242:245], v[156:159], v[48:51]
	v_mfma_f32_16x16x32_bf16 v[36:39], v[234:237], v[192:195], v[36:39]
	v_mfma_f32_16x16x32_bf16 v[32:35], v[242:245], v[192:195], v[32:35]
	v_mfma_f32_16x16x32_bf16 v[20:23], v[234:237], v[226:229], v[20:23]
	v_mfma_f32_16x16x32_bf16 v[16:19], v[242:245], v[226:229], v[16:19]
	s_barrier
	ds_read_b128 v[124:127], v217 offset:32768
	ds_read_b128 v[128:131], v217 offset:33792
	ds_read_b128 v[132:135], v217 offset:34816
	ds_read_b128 v[136:139], v217 offset:35840
	s_mov_b32 m0, s60
	ds_read_b128 v[140:143], v186 offset:32768
	ds_read_b128 v[148:151], v186 offset:33792
	ds_read_b128 v[152:155], v186 offset:34816
	ds_read_b128 v[156:159], v186 offset:35840
	ds_read_b128 v[188:191], v186 offset:36864
	ds_read_b128 v[192:195], v186 offset:37888
	ds_read_b128 v[222:225], v186 offset:38912
	global_load_lds_dwordx4 v0, s[54:55]
	s_mov_b32 m0, s61
	ds_read_b128 v[226:229], v186 offset:39936
	global_load_lds_dwordx4 v2, s[54:55]
	s_waitcnt vmcnt(10) lgkmcnt(8)
	s_barrier
	s_waitcnt lgkmcnt(0)
	s_waitcnt lgkmcnt(0)
	v_mfma_f32_16x16x32_bf16 v[164:167], v[124:127], v[140:143], v[164:167]
	v_mfma_f32_16x16x32_bf16 v[160:163], v[132:135], v[140:143], v[160:163]
	v_mfma_f32_16x16x32_bf16 v[116:119], v[124:127], v[152:155], v[116:119]
	v_mfma_f32_16x16x32_bf16 v[112:115], v[132:135], v[152:155], v[112:115]
	v_mfma_f32_16x16x32_bf16 v[100:103], v[124:127], v[188:191], v[100:103]
	v_mfma_f32_16x16x32_bf16 v[96:99], v[132:135], v[188:191], v[96:99]
	v_mfma_f32_16x16x32_bf16 v[84:87], v[124:127], v[222:225], v[84:87]
	v_mfma_f32_16x16x32_bf16 v[80:83], v[132:135], v[222:225], v[80:83]
	v_mfma_f32_16x16x32_bf16 v[164:167], v[128:131], v[148:151], v[164:167]
	v_mfma_f32_16x16x32_bf16 v[160:163], v[136:139], v[148:151], v[160:163]
	v_mfma_f32_16x16x32_bf16 v[116:119], v[128:131], v[156:159], v[116:119]
	v_mfma_f32_16x16x32_bf16 v[112:115], v[136:139], v[156:159], v[112:115]
	v_mfma_f32_16x16x32_bf16 v[100:103], v[128:131], v[192:195], v[100:103]
	v_mfma_f32_16x16x32_bf16 v[96:99], v[136:139], v[192:195], v[96:99]
	v_mfma_f32_16x16x32_bf16 v[84:87], v[128:131], v[226:229], v[84:87]
	v_mfma_f32_16x16x32_bf16 v[80:83], v[136:139], v[226:229], v[80:83]
	s_barrier
	s_add_i32 m0, s57, 0x18000
	ds_read_b128 v[230:233], v217 offset:49152
	ds_read_b128 v[234:237], v217 offset:50176
	ds_read_b128 v[238:241], v217 offset:51200
	s_add_u32 s98, s52, 0x80
	s_addc_u32 s99, s53, 0
	global_load_lds_dwordx4 v0, s[98:99]
	s_add_i32 m0, s57, 0x1a000
	ds_read_b128 v[242:245], v217 offset:52224
	global_load_lds_dwordx4 v2, s[98:99]
	s_waitcnt vmcnt(10)
	s_barrier
	s_waitcnt lgkmcnt(0)
	s_waitcnt lgkmcnt(0)
	v_mfma_f32_16x16x32_bf16 v[144:147], v[230:233], v[140:143], v[144:147]
	v_mfma_f32_16x16x32_bf16 v[120:123], v[238:241], v[140:143], v[120:123]
	v_mfma_f32_16x16x32_bf16 v[108:111], v[230:233], v[152:155], v[108:111]
	v_mfma_f32_16x16x32_bf16 v[104:107], v[238:241], v[152:155], v[104:107]
	v_mfma_f32_16x16x32_bf16 v[92:95], v[230:233], v[188:191], v[92:95]
	v_mfma_f32_16x16x32_bf16 v[88:91], v[238:241], v[188:191], v[88:91]
	v_mfma_f32_16x16x32_bf16 v[76:79], v[230:233], v[222:225], v[76:79]
	v_mfma_f32_16x16x32_bf16 v[72:75], v[238:241], v[222:225], v[72:75]
	v_mfma_f32_16x16x32_bf16 v[144:147], v[234:237], v[148:151], v[144:147]
	v_mfma_f32_16x16x32_bf16 v[120:123], v[242:245], v[148:151], v[120:123]
	v_mfma_f32_16x16x32_bf16 v[108:111], v[234:237], v[156:159], v[108:111]
	v_mfma_f32_16x16x32_bf16 v[104:107], v[242:245], v[156:159], v[104:107]
	v_mfma_f32_16x16x32_bf16 v[92:95], v[234:237], v[192:195], v[92:95]
	v_mfma_f32_16x16x32_bf16 v[88:91], v[242:245], v[192:195], v[88:91]
	v_mfma_f32_16x16x32_bf16 v[76:79], v[234:237], v[226:229], v[76:79]
	v_mfma_f32_16x16x32_bf16 v[72:75], v[242:245], v[226:229], v[72:75]
	s_mov_b32 m0, s62
	s_barrier
	ds_read_b128 v[140:143], v186 offset:49152
	ds_read_b128 v[148:151], v186 offset:50176
	ds_read_b128 v[152:155], v186 offset:51200
	ds_read_b128 v[156:159], v186 offset:52224
	ds_read_b128 v[188:191], v186 offset:53248
	ds_read_b128 v[192:195], v186 offset:54272
	ds_read_b128 v[222:225], v186 offset:55296
	s_add_u32 s98, s54, 0xfffc0080
	s_addc_u32 s99, s55, -1
	global_load_lds_dwordx4 v0, s[98:99]
	s_mov_b32 m0, s63
	ds_read_b128 v[226:229], v186 offset:56320
	global_load_lds_dwordx4 v2, s[98:99]
	s_barrier
	s_waitcnt lgkmcnt(0)
	s_waitcnt lgkmcnt(0)
	v_mfma_f32_16x16x32_bf16 v[60:63], v[124:127], v[140:143], v[60:63]
	v_mfma_f32_16x16x32_bf16 v[56:59], v[132:135], v[140:143], v[56:59]
	v_mfma_f32_16x16x32_bf16 v[44:47], v[124:127], v[152:155], v[44:47]
	v_mfma_f32_16x16x32_bf16 v[40:43], v[132:135], v[152:155], v[40:43]
	v_mfma_f32_16x16x32_bf16 v[28:31], v[124:127], v[188:191], v[28:31]
	v_mfma_f32_16x16x32_bf16 v[24:27], v[132:135], v[188:191], v[24:27]
	v_mfma_f32_16x16x32_bf16 v[12:15], v[124:127], v[222:225], v[12:15]
	v_mfma_f32_16x16x32_bf16 v[8:11], v[132:135], v[222:225], v[8:11]
	v_mfma_f32_16x16x32_bf16 v[60:63], v[128:131], v[148:151], v[60:63]
	v_mfma_f32_16x16x32_bf16 v[56:59], v[136:139], v[148:151], v[56:59]
	v_mfma_f32_16x16x32_bf16 v[44:47], v[128:131], v[156:159], v[44:47]
	v_mfma_f32_16x16x32_bf16 v[40:43], v[136:139], v[156:159], v[40:43]
	v_mfma_f32_16x16x32_bf16 v[28:31], v[128:131], v[192:195], v[28:31]
	v_mfma_f32_16x16x32_bf16 v[24:27], v[136:139], v[192:195], v[24:27]
	v_mfma_f32_16x16x32_bf16 v[12:15], v[128:131], v[226:229], v[12:15]
	v_mfma_f32_16x16x32_bf16 v[8:11], v[136:139], v[226:229], v[8:11]
	s_barrier
	s_add_i32 m0, s57, 0x1c000
	s_add_u32 s52, s52, 0x40080
	s_addc_u32 s53, s53, 0
	global_load_lds_dwordx4 v0, s[52:53]
	s_add_i32 m0, s57, 0x1e000
	s_add_i32 s73, s73, 2
	global_load_lds_dwordx4 v2, s[52:53]
	s_add_u32 s71, s71, 0x100
	s_addc_u32 s72, s72, 0
	s_add_u32 s50, s50, 0x100
	s_addc_u32 s51, s51, 0
	s_cmp_gt_u32 s73, 13
	s_cbranch_scc1 .LrotX_78
	s_cmp_lg_u32 s73, 12
	s_cselect_b64 s[52:53], -1, 0
	s_add_u32 s12, s50, 0xfffc0080
	s_addc_u32 s26, s51, -1
	s_and_b64 s[52:53], s[52:53], exec
	s_cselect_b32 s55, s26, s43
	s_cselect_b32 s54, s12, s42
	s_cselect_b32 s53, s72, s15
	s_cselect_b32 s52, s71, s69
;     __device__ __forceinline__ void prep(int pm, int par, LAS unsigned char* lds) const { if (fold) prep_rowstats(stat, pm, par, lds); }
;     __device__ __forceinline__ void prep(int pm, int par, LAS unsigned char* lds) const { if (!ident) prep_rowstats(stat, pm, par, lds); }
;     __device__ __forceinline__ void prep(int pm, int par, LAS unsigned char* lds) const { prep_rowstats(stat, pm, par, lds); }
; #define G_STAGE(bufoff, gbase) do { _Pragma("unroll") for (int _i = 0; _i < 2; ++_i) \
;         __builtin_amdgcn_global_load_lds((const unsigned*)((const char*)(gbase) + voff[_i]), (LAS unsigned*)(lds + (bufoff) + ldsw + _i * 8192), 16, 0, 0); } while (0)
; #define G_MMA(ai, bj, At, Bt) do { __builtin_amdgcn_s_setprio(1); _Pragma("unroll") for (int m = 0; m < 4; ++m) _Pragma("unroll") for (int n = 0; n < 2; ++n) _Pragma("unroll") for (int k = 0; k < 2; ++k) \
;         acc[ai][bj][m][n] = MFMA16(Bt[n][k], At[m][k], acc[ai][bj][m][n]); __builtin_amdgcn_s_setprio(0); } while (0)
; #define G_WAIT_V(n) asm volatile("s_waitcnt vmcnt(" #n ")" ::: "memory")
; #define G_BAR __builtin_amdgcn_s_barrier()
; template <class Epi>
; __device__ __forceinline__ void gemm_phase(LAS unsigned char* lds, const bf16_t* Ag, const bf16_t* Btg, const int K, const int nM, const int nN, const Epi& E) {
;     ...
;         for (int t = 0; t < nt; t += 2) {
;             const bool last = (t == nt - 2);
;             const char* a1 = cA + (size_t)(t + 1) * kstep;
;             const char* a2 = last ? nA : cA + (size_t)(t + 2) * kstep; const char* b2 = last ? nB : cB + (size_t)(t + 2) * kstep;
;             const char* a3 = a2 + kstep; const char* b3 = b2 + kstep;
;             if (last && has_next && pmn != pm) E.prep(pmn, par ^ 1, lds);
;     ...
;             G_STAGE(G_SB(1, 1), b3 + hstep);
;             G_WAIT_V(6); G_BAR; G_MMA(1, 1, At, B1); G_BAR;
;         }
.LrotX_78:
	s_waitcnt vmcnt(10)
	s_barrier
	v_mfma_f32_16x16x32_bf16 v[68:71], v[230:233], v[140:143], v[68:71]
	v_mfma_f32_16x16x32_bf16 v[64:67], v[238:241], v[140:143], v[64:67]
	v_mfma_f32_16x16x32_bf16 v[52:55], v[230:233], v[152:155], v[52:55]
	v_mfma_f32_16x16x32_bf16 v[48:51], v[238:241], v[152:155], v[48:51]
	v_mfma_f32_16x16x32_bf16 v[36:39], v[230:233], v[188:191], v[36:39]
	v_mfma_f32_16x16x32_bf16 v[32:35], v[238:241], v[188:191], v[32:35]
	v_mfma_f32_16x16x32_bf16 v[20:23], v[230:233], v[222:225], v[20:23]
	v_mfma_f32_16x16x32_bf16 v[16:19], v[238:241], v[222:225], v[16:19]
	v_mfma_f32_16x16x32_bf16 v[68:71], v[234:237], v[148:151], v[68:71]
	v_mfma_f32_16x16x32_bf16 v[64:67], v[242:245], v[148:151], v[64:67]
	v_mfma_f32_16x16x32_bf16 v[52:55], v[234:237], v[156:159], v[52:55]
	v_mfma_f32_16x16x32_bf16 v[48:51], v[242:245], v[156:159], v[48:51]
	v_mfma_f32_16x16x32_bf16 v[36:39], v[234:237], v[192:195], v[36:39]
	v_mfma_f32_16x16x32_bf16 v[32:35], v[242:245], v[192:195], v[32:35]
	v_mfma_f32_16x16x32_bf16 v[20:23], v[234:237], v[226:229], v[20:23]
	v_mfma_f32_16x16x32_bf16 v[16:19], v[242:245], v[226:229], v[16:19]
	s_cmp_gt_u32 s73, 13
	s_barrier
	s_cbranch_scc1 .LBB0_82
	s_cmp_lg_u32 s73, 12
	s_cbranch_scc1 .LmainW_78

; #define G_STAGE(bufoff, gbase) do { _Pragma("unroll") for (int _i = 0; _i < 2; ++_i) \
;         __builtin_amdgcn_global_load_lds((const unsigned*)((const char*)(gbase) + voff[_i]), (LAS unsigned*)(lds + (bufoff) + ldsw + _i * 8192), 16, 0, 0); } while (0)
; #define G_LDA(dst, b, h) do { _Pragma("unroll") for (int m = 0; m < 4; ++m) _Pragma("unroll") for (int k = 0; k < 2; ++k) dst[m][k] = *(const LAS bf16x8*)(lds + G_SA(b, h) + aoff + m * 2048 + k * 1024); } while (0)
; #define G_LDB(dst, b, h) do { _Pragma("unroll") for (int n = 0; n < 2; ++n) _Pragma("unroll") for (int k = 0; k < 2; ++k) dst[n][k] = *(const LAS bf16x8*)(lds + G_SB(b, h) + boff + n * 2048 + k * 1024); } while (0)
; #define G_MMA(ai, bj, At, Bt) do { __builtin_amdgcn_s_setprio(1); _Pragma("unroll") for (int m = 0; m < 4; ++m) _Pragma("unroll") for (int n = 0; n < 2; ++n) _Pragma("unroll") for (int k = 0; k < 2; ++k) \
;         acc[ai][bj][m][n] = MFMA16(Bt[n][k], At[m][k], acc[ai][bj][m][n]); __builtin_amdgcn_s_setprio(0); } while (0)
; #define G_WAIT_V(n) asm volatile("s_waitcnt vmcnt(" #n ")" ::: "memory")
; #define G_WAIT_L(n) asm volatile("s_waitcnt lgkmcnt(" #n ")" ::: "memory")
; #define G_BAR __builtin_amdgcn_s_barrier()
; #define G_SCHED __builtin_amdgcn_sched_barrier(0)
; template <class Epi>
; __device__ __forceinline__ void gemm_phase(LAS unsigned char* lds, const bf16_t* Ag, const bf16_t* Btg, const int K, const int nM, const int nN, const Epi& E) {
;     ...
;             G_LDB(B0, 0, 0); G_SCHED; G_LDA(At, 0, 0); G_STAGE(G_SA(1, 1), a1 + hstep);
;             G_WAIT_L(8); G_BAR; G_WAIT_L(0); G_MMA(0, 0, At, B0); G_BAR; G_SCHED;
;             G_LDB(B1, 0, 1); G_STAGE(G_SB(0, 0), b2);
;             G_BAR; G_WAIT_L(0); G_MMA(0, 1, At, B1); G_BAR;
;             G_LDA(At, 0, 1); G_STAGE(G_SA(0, 0), a2);
;             G_BAR; G_WAIT_L(0); G_MMA(1, 0, At, B0); G_BAR; G_SCHED;
;             G_STAGE(G_SB(0, 1), b2 + hstep);
;             G_WAIT_V(6); G_BAR; G_MMA(1, 1, At, B1); G_BAR;
.LmainW_153:
	ds_read_b128 v[144:147], v217
	ds_read_b128 v[148:151], v217 offset:1024
	ds_read_b128 v[152:155], v217 offset:2048
	ds_read_b128 v[156:159], v217 offset:3072
	s_add_i32 m0, s72, 0xc000
	ds_read_b128 v[160:163], v230
	ds_read_b128 v[164:167], v230 offset:1024
	ds_read_b128 v[168:171], v230 offset:2048
	ds_read_b128 v[172:175], v230 offset:3072
	ds_read_b128 v[180:183], v230 offset:4096
	ds_read_b128 v[184:187], v230 offset:5120
	ds_read_b128 v[188:191], v230 offset:6144
	global_load_lds_dwordx4 v138, s[64:65]
	s_add_i32 m0, s72, 0xe000
	ds_read_b128 v[192:195], v230 offset:7168
	global_load_lds_dwordx4 v136, s[64:65]
	s_waitcnt vmcnt(10) lgkmcnt(8)
	s_barrier
	s_waitcnt lgkmcnt(0)
	s_waitcnt lgkmcnt(0)
	v_mfma_f32_16x16x32_bf16 v[132:135], v[144:147], v[160:163], v[132:135]
	v_mfma_f32_16x16x32_bf16 v[128:131], v[152:155], v[160:163], v[128:131]
	v_mfma_f32_16x16x32_bf16 v[116:119], v[144:147], v[168:171], v[116:119]
	v_mfma_f32_16x16x32_bf16 v[112:115], v[152:155], v[168:171], v[112:115]
	v_mfma_f32_16x16x32_bf16 v[100:103], v[144:147], v[180:183], v[100:103]
	v_mfma_f32_16x16x32_bf16 v[96:99], v[152:155], v[180:183], v[96:99]
	v_mfma_f32_16x16x32_bf16 v[84:87], v[144:147], v[188:191], v[84:87]
	v_mfma_f32_16x16x32_bf16 v[80:83], v[152:155], v[188:191], v[80:83]
	v_mfma_f32_16x16x32_bf16 v[132:135], v[148:151], v[164:167], v[132:135]
	v_mfma_f32_16x16x32_bf16 v[128:131], v[156:159], v[164:167], v[128:131]
	v_mfma_f32_16x16x32_bf16 v[116:119], v[148:151], v[172:175], v[116:119]
	v_mfma_f32_16x16x32_bf16 v[112:115], v[156:159], v[172:175], v[112:115]
	v_mfma_f32_16x16x32_bf16 v[100:103], v[148:151], v[184:187], v[100:103]
	v_mfma_f32_16x16x32_bf16 v[96:99], v[156:159], v[184:187], v[96:99]
	v_mfma_f32_16x16x32_bf16 v[84:87], v[148:151], v[192:195], v[84:87]
	v_mfma_f32_16x16x32_bf16 v[80:83], v[156:159], v[192:195], v[80:83]
	s_barrier
	s_add_i32 m0, s21, 0x10000
	ds_read_b128 v[232:235], v217 offset:16384
	ds_read_b128 v[236:239], v217 offset:17408
	ds_read_b128 v[240:243], v217 offset:18432
	global_load_lds_dwordx4 v0, s[68:69]
	s_add_i32 m0, s21, 0x12000
	ds_read_b128 v[244:247], v217 offset:19456
	global_load_lds_dwordx4 v2, s[68:69]
	s_waitcnt vmcnt(10)
	s_barrier
	s_waitcnt lgkmcnt(0)
	s_waitcnt lgkmcnt(0)
	v_mfma_f32_16x16x32_bf16 v[124:127], v[232:235], v[160:163], v[124:127]
	v_mfma_f32_16x16x32_bf16 v[120:123], v[240:243], v[160:163], v[120:123]
	v_mfma_f32_16x16x32_bf16 v[108:111], v[232:235], v[168:171], v[108:111]
	v_mfma_f32_16x16x32_bf16 v[104:107], v[240:243], v[168:171], v[104:107]
	v_mfma_f32_16x16x32_bf16 v[92:95], v[232:235], v[180:183], v[92:95]
	v_mfma_f32_16x16x32_bf16 v[88:91], v[240:243], v[180:183], v[88:91]
	v_mfma_f32_16x16x32_bf16 v[76:79], v[232:235], v[188:191], v[76:79]
	v_mfma_f32_16x16x32_bf16 v[72:75], v[240:243], v[188:191], v[72:75]
	v_mfma_f32_16x16x32_bf16 v[124:127], v[236:239], v[164:167], v[124:127]
	v_mfma_f32_16x16x32_bf16 v[120:123], v[244:247], v[164:167], v[120:123]
	v_mfma_f32_16x16x32_bf16 v[108:111], v[236:239], v[172:175], v[108:111]
	v_mfma_f32_16x16x32_bf16 v[104:107], v[244:247], v[172:175], v[104:107]
	v_mfma_f32_16x16x32_bf16 v[92:95], v[236:239], v[184:187], v[92:95]
	v_mfma_f32_16x16x32_bf16 v[88:91], v[244:247], v[184:187], v[88:91]
	v_mfma_f32_16x16x32_bf16 v[76:79], v[236:239], v[192:195], v[76:79]
	v_mfma_f32_16x16x32_bf16 v[72:75], v[244:247], v[192:195], v[72:75]
	s_mov_b32 m0, s72
	s_barrier
	ds_read_b128 v[160:163], v230 offset:16384
	ds_read_b128 v[164:167], v230 offset:17408
	ds_read_b128 v[168:171], v230 offset:18432
	ds_read_b128 v[172:175], v230 offset:19456
	ds_read_b128 v[180:183], v230 offset:20480
	ds_read_b128 v[184:187], v230 offset:21504
	ds_read_b128 v[188:191], v230 offset:22528
	global_load_lds_dwordx4 v0, s[70:71]
	s_mov_b32 m0, s73
	ds_read_b128 v[192:195], v230 offset:23552
	global_load_lds_dwordx4 v2, s[70:71]
	s_barrier
	s_waitcnt lgkmcnt(0)
	s_waitcnt lgkmcnt(0)
	v_mfma_f32_16x16x32_bf16 v[68:71], v[144:147], v[160:163], v[68:71]
	v_mfma_f32_16x16x32_bf16 v[64:67], v[152:155], v[160:163], v[64:67]
	v_mfma_f32_16x16x32_bf16 v[52:55], v[144:147], v[168:171], v[52:55]
	v_mfma_f32_16x16x32_bf16 v[48:51], v[152:155], v[168:171], v[48:51]
	v_mfma_f32_16x16x32_bf16 v[36:39], v[144:147], v[180:183], v[36:39]
	v_mfma_f32_16x16x32_bf16 v[32:35], v[152:155], v[180:183], v[32:35]
	v_mfma_f32_16x16x32_bf16 v[20:23], v[144:147], v[188:191], v[20:23]
	v_mfma_f32_16x16x32_bf16 v[16:19], v[152:155], v[188:191], v[16:19]
	v_mfma_f32_16x16x32_bf16 v[68:71], v[148:151], v[164:167], v[68:71]
	v_mfma_f32_16x16x32_bf16 v[64:67], v[156:159], v[164:167], v[64:67]
	v_mfma_f32_16x16x32_bf16 v[52:55], v[148:151], v[172:175], v[52:55]
	v_mfma_f32_16x16x32_bf16 v[48:51], v[156:159], v[172:175], v[48:51]
	v_mfma_f32_16x16x32_bf16 v[36:39], v[148:151], v[184:187], v[36:39]
	v_mfma_f32_16x16x32_bf16 v[32:35], v[156:159], v[184:187], v[32:35]
	v_mfma_f32_16x16x32_bf16 v[20:23], v[148:151], v[192:195], v[20:23]
	v_mfma_f32_16x16x32_bf16 v[16:19], v[156:159], v[192:195], v[16:19]
	s_barrier
	s_add_i32 m0, s21, 0x14000
	s_add_u32 s64, s68, 0x40000
	s_addc_u32 s65, s69, 0
	global_load_lds_dwordx4 v0, s[64:65]
	s_add_i32 m0, s21, 0x16000
	s_add_u32 s98, s70, 0x40000
	s_addc_u32 s99, s71, 0
	global_load_lds_dwordx4 v2, s[64:65]
	s_waitcnt vmcnt(10)
	s_barrier
;     __device__ __forceinline__ void prep(int pm, int par, LAS unsigned char* lds) const { if (fold) prep_rowstats(stat, pm, par, lds); }
;     __device__ __forceinline__ void prep(int pm, int par, LAS unsigned char* lds) const { if (!ident) prep_rowstats(stat, pm, par, lds); }
;     __device__ __forceinline__ void prep(int pm, int par, LAS unsigned char* lds) const { prep_rowstats(stat, pm, par, lds); }
; #define G_STAGE(bufoff, gbase) do { _Pragma("unroll") for (int _i = 0; _i < 2; ++_i) \
;         __builtin_amdgcn_global_load_lds((const unsigned*)((const char*)(gbase) + voff[_i]), (LAS unsigned*)(lds + (bufoff) + ldsw + _i * 8192), 16, 0, 0); } while (0)
; #define G_WAIT_V(n) asm volatile("s_waitcnt vmcnt(" #n ")" ::: "memory")
; #define G_WAIT_L(n) asm volatile("s_waitcnt lgkmcnt(" #n ")" ::: "memory")
; #define G_BAR __builtin_amdgcn_s_barrier()
; template <class Epi>
; __device__ __forceinline__ void gemm_phase(LAS unsigned char* lds, const bf16_t* Ag, const bf16_t* Btg, const int K, const int nM, const int nN, const Epi& E) {
;     ...
;             const char* a2 = last ? nA : cA + (size_t)(t + 2) * kstep; const char* b2 = last ? nB : cB + (size_t)(t + 2) * kstep;
;             const char* a3 = a2 + kstep; const char* b3 = b2 + kstep;
;             if (last && has_next && pmn != pm) E.prep(pmn, par ^ 1, lds);
;             G_LDB(B0, 0, 0); G_SCHED; G_LDA(At, 0, 0); G_STAGE(G_SA(1, 1), a1 + hstep);
;             G_WAIT_L(8); G_BAR; G_WAIT_L(0); G_MMA(0, 0, At, B0); G_BAR; G_SCHED;
;             G_LDB(B1, 0, 1); G_STAGE(G_SB(0, 0), b2);
;             G_BAR; G_WAIT_L(0); G_MMA(0, 1, At, B1); G_BAR;
;             G_LDA(At, 0, 1); G_STAGE(G_SA(0, 0), a2);
;             G_BAR; G_WAIT_L(0); G_MMA(1, 0, At, B0); G_BAR; G_SCHED;
;             G_STAGE(G_SB(0, 1), b2 + hstep);
;             G_WAIT_V(6); G_BAR; G_MMA(1, 1, At, B1); G_BAR;
;             G_LDB(B0, 1, 0); G_SCHED; G_LDA(At, 1, 0); G_STAGE(G_SA(0, 1), a2 + hstep);
;             G_WAIT_L(8); G_BAR; G_WAIT_L(0); G_MMA(0, 0, At, B0); G_BAR; G_SCHED;
;             G_LDB(B1, 1, 1); G_STAGE(G_SB(1, 0), b3);
;             G_BAR; G_WAIT_L(0); G_MMA(0, 1, At, B1); G_BAR;
;             G_LDA(At, 1, 1); G_STAGE(G_SA(1, 0), a3);
;             G_BAR; G_WAIT_L(0); G_MMA(1, 0, At, B0); G_BAR; G_SCHED;
;             G_STAGE(G_SB(1, 1), b3 + hstep);
;             G_WAIT_V(6); G_BAR; G_MMA(1, 1, At, B1); G_BAR;
	v_mfma_f32_16x16x32_bf16 v[60:63], v[232:235], v[160:163], v[60:63]
	v_mfma_f32_16x16x32_bf16 v[56:59], v[240:243], v[160:163], v[56:59]
	v_mfma_f32_16x16x32_bf16 v[44:47], v[232:235], v[168:171], v[44:47]
	v_mfma_f32_16x16x32_bf16 v[40:43], v[240:243], v[168:171], v[40:43]
	v_mfma_f32_16x16x32_bf16 v[28:31], v[232:235], v[180:183], v[28:31]
	v_mfma_f32_16x16x32_bf16 v[24:27], v[240:243], v[180:183], v[24:27]
	v_mfma_f32_16x16x32_bf16 v[12:15], v[232:235], v[188:191], v[12:15]
	v_mfma_f32_16x16x32_bf16 v[8:11], v[240:243], v[188:191], v[8:11]
	v_mfma_f32_16x16x32_bf16 v[60:63], v[236:239], v[164:167], v[60:63]
	v_mfma_f32_16x16x32_bf16 v[56:59], v[244:247], v[164:167], v[56:59]
	v_mfma_f32_16x16x32_bf16 v[44:47], v[236:239], v[172:175], v[44:47]
	v_mfma_f32_16x16x32_bf16 v[40:43], v[244:247], v[172:175], v[40:43]
	v_mfma_f32_16x16x32_bf16 v[28:31], v[236:239], v[184:187], v[28:31]
	v_mfma_f32_16x16x32_bf16 v[24:27], v[244:247], v[184:187], v[24:27]
	v_mfma_f32_16x16x32_bf16 v[12:15], v[236:239], v[192:195], v[12:15]
	v_mfma_f32_16x16x32_bf16 v[8:11], v[244:247], v[192:195], v[8:11]
	s_barrier
	ds_read_b128 v[144:147], v217 offset:32768
	ds_read_b128 v[148:151], v217 offset:33792
	ds_read_b128 v[152:155], v217 offset:34816
	ds_read_b128 v[156:159], v217 offset:35840
	s_mov_b32 m0, s74
	ds_read_b128 v[160:163], v230 offset:32768
	ds_read_b128 v[164:167], v230 offset:33792
	ds_read_b128 v[168:171], v230 offset:34816
	ds_read_b128 v[172:175], v230 offset:35840
	ds_read_b128 v[180:183], v230 offset:36864
	ds_read_b128 v[184:187], v230 offset:37888
	ds_read_b128 v[188:191], v230 offset:38912
	global_load_lds_dwordx4 v0, s[98:99]
	s_mov_b32 m0, s75
	ds_read_b128 v[192:195], v230 offset:39936
	global_load_lds_dwordx4 v2, s[98:99]
	s_waitcnt vmcnt(10) lgkmcnt(8)
	s_barrier
	s_waitcnt lgkmcnt(0)
	s_waitcnt lgkmcnt(0)
	v_mfma_f32_16x16x32_bf16 v[132:135], v[144:147], v[160:163], v[132:135]
	v_mfma_f32_16x16x32_bf16 v[128:131], v[152:155], v[160:163], v[128:131]
	v_mfma_f32_16x16x32_bf16 v[116:119], v[144:147], v[168:171], v[116:119]
	v_mfma_f32_16x16x32_bf16 v[112:115], v[152:155], v[168:171], v[112:115]
	v_mfma_f32_16x16x32_bf16 v[100:103], v[144:147], v[180:183], v[100:103]
	v_mfma_f32_16x16x32_bf16 v[96:99], v[152:155], v[180:183], v[96:99]
	v_mfma_f32_16x16x32_bf16 v[84:87], v[144:147], v[188:191], v[84:87]
	v_mfma_f32_16x16x32_bf16 v[80:83], v[152:155], v[188:191], v[80:83]
	v_mfma_f32_16x16x32_bf16 v[132:135], v[148:151], v[164:167], v[132:135]
	v_mfma_f32_16x16x32_bf16 v[128:131], v[156:159], v[164:167], v[128:131]
	v_mfma_f32_16x16x32_bf16 v[116:119], v[148:151], v[172:175], v[116:119]
	v_mfma_f32_16x16x32_bf16 v[112:115], v[156:159], v[172:175], v[112:115]
	v_mfma_f32_16x16x32_bf16 v[100:103], v[148:151], v[184:187], v[100:103]
	v_mfma_f32_16x16x32_bf16 v[96:99], v[156:159], v[184:187], v[96:99]
	v_mfma_f32_16x16x32_bf16 v[84:87], v[148:151], v[192:195], v[84:87]
	v_mfma_f32_16x16x32_bf16 v[80:83], v[156:159], v[192:195], v[80:83]
	s_barrier
	s_add_i32 m0, s21, 0x18000
	ds_read_b128 v[232:235], v217 offset:49152
	ds_read_b128 v[236:239], v217 offset:50176
	ds_read_b128 v[240:243], v217 offset:51200
	s_add_u32 s98, s68, 0x80
	s_addc_u32 s99, s69, 0
	global_load_lds_dwordx4 v0, s[98:99]
	s_add_i32 m0, s21, 0x1a000
	ds_read_b128 v[244:247], v217 offset:52224
	global_load_lds_dwordx4 v2, s[98:99]
	s_waitcnt vmcnt(10)
	s_barrier
	s_waitcnt lgkmcnt(0)
	s_waitcnt lgkmcnt(0)
	v_mfma_f32_16x16x32_bf16 v[124:127], v[232:235], v[160:163], v[124:127]
	v_mfma_f32_16x16x32_bf16 v[120:123], v[240:243], v[160:163], v[120:123]
	v_mfma_f32_16x16x32_bf16 v[108:111], v[232:235], v[168:171], v[108:111]
	v_mfma_f32_16x16x32_bf16 v[104:107], v[240:243], v[168:171], v[104:107]
	v_mfma_f32_16x16x32_bf16 v[92:95], v[232:235], v[180:183], v[92:95]
	v_mfma_f32_16x16x32_bf16 v[88:91], v[240:243], v[180:183], v[88:91]
	v_mfma_f32_16x16x32_bf16 v[76:79], v[232:235], v[188:191], v[76:79]
	v_mfma_f32_16x16x32_bf16 v[72:75], v[240:243], v[188:191], v[72:75]
	v_mfma_f32_16x16x32_bf16 v[124:127], v[236:239], v[164:167], v[124:127]
	v_mfma_f32_16x16x32_bf16 v[120:123], v[244:247], v[164:167], v[120:123]
	v_mfma_f32_16x16x32_bf16 v[108:111], v[236:239], v[172:175], v[108:111]
	v_mfma_f32_16x16x32_bf16 v[104:107], v[244:247], v[172:175], v[104:107]
	v_mfma_f32_16x16x32_bf16 v[92:95], v[236:239], v[184:187], v[92:95]
	v_mfma_f32_16x16x32_bf16 v[88:91], v[244:247], v[184:187], v[88:91]
	v_mfma_f32_16x16x32_bf16 v[76:79], v[236:239], v[192:195], v[76:79]
	v_mfma_f32_16x16x32_bf16 v[72:75], v[244:247], v[192:195], v[72:75]
	s_mov_b32 m0, s76
	s_barrier
	ds_read_b128 v[160:163], v230 offset:49152
	ds_read_b128 v[164:167], v230 offset:50176
	ds_read_b128 v[168:171], v230 offset:51200
	ds_read_b128 v[172:175], v230 offset:52224
	ds_read_b128 v[180:183], v230 offset:53248
	ds_read_b128 v[184:187], v230 offset:54272
	ds_read_b128 v[188:191], v230 offset:55296
	s_add_u32 s98, s70, 0x80
	s_addc_u32 s99, s71, 0
	global_load_lds_dwordx4 v0, s[98:99]
	s_mov_b32 m0, s77
	ds_read_b128 v[192:195], v230 offset:56320
	global_load_lds_dwordx4 v2, s[98:99]
	s_barrier
	s_waitcnt lgkmcnt(0)
	s_waitcnt lgkmcnt(0)
	v_mfma_f32_16x16x32_bf16 v[68:71], v[144:147], v[160:163], v[68:71]
	v_mfma_f32_16x16x32_bf16 v[64:67], v[152:155], v[160:163], v[64:67]
	v_mfma_f32_16x16x32_bf16 v[52:55], v[144:147], v[168:171], v[52:55]
	v_mfma_f32_16x16x32_bf16 v[48:51], v[152:155], v[168:171], v[48:51]
	v_mfma_f32_16x16x32_bf16 v[36:39], v[144:147], v[180:183], v[36:39]
	v_mfma_f32_16x16x32_bf16 v[32:35], v[152:155], v[180:183], v[32:35]
	v_mfma_f32_16x16x32_bf16 v[20:23], v[144:147], v[188:191], v[20:23]
	v_mfma_f32_16x16x32_bf16 v[16:19], v[152:155], v[188:191], v[16:19]
	v_mfma_f32_16x16x32_bf16 v[68:71], v[148:151], v[164:167], v[68:71]
	v_mfma_f32_16x16x32_bf16 v[64:67], v[156:159], v[164:167], v[64:67]
	v_mfma_f32_16x16x32_bf16 v[52:55], v[148:151], v[172:175], v[52:55]
	v_mfma_f32_16x16x32_bf16 v[48:51], v[156:159], v[172:175], v[48:51]
	v_mfma_f32_16x16x32_bf16 v[36:39], v[148:151], v[184:187], v[36:39]
	v_mfma_f32_16x16x32_bf16 v[32:35], v[156:159], v[184:187], v[32:35]
	v_mfma_f32_16x16x32_bf16 v[20:23], v[148:151], v[192:195], v[20:23]
	v_mfma_f32_16x16x32_bf16 v[16:19], v[156:159], v[192:195], v[16:19]
	s_barrier
	s_add_i32 m0, s21, 0x1c000
	s_add_u32 s64, s68, 0x40080
	s_addc_u32 s65, s69, 0
	global_load_lds_dwordx4 v0, s[64:65]
	s_add_i32 m0, s21, 0x1e000
	s_add_i32 s42, s42, 2
	global_load_lds_dwordx4 v2, s[64:65]
	s_add_u32 s57, s57, 0x100
	s_addc_u32 s61, s61, 0
	s_mov_b64 s[64:65], s[66:67]
	s_cmp_gt_u32 s42, 13
	s_cbranch_scc1 .LrotX_153
	s_cmp_lg_u32 s42, 12
	s_cselect_b64 s[68:69], -1, 0
	s_add_u32 s66, s64, 0x100
	s_addc_u32 s67, s65, 0
	s_and_b64 s[68:69], s[68:69], exec
	s_cselect_b32 s71, s67, s55
	s_cselect_b32 s70, s66, s54
	s_cselect_b32 s69, s61, s14
	s_cselect_b32 s68, s57, s15
; #define G_STAGE(bufoff, gbase) do { _Pragma("unroll") for (int _i = 0; _i < 2; ++_i) \
;         __builtin_amdgcn_global_load_lds((const unsigned*)((const char*)(gbase) + voff[_i]), (LAS unsigned*)(lds + (bufoff) + ldsw + _i * 8192), 16, 0, 0); } while (0)
; #define G_MMA(ai, bj, At, Bt) do { __builtin_amdgcn_s_setprio(1); _Pragma("unroll") for (int m = 0; m < 4; ++m) _Pragma("unroll") for (int n = 0; n < 2; ++n) _Pragma("unroll") for (int k = 0; k < 2; ++k) \
;         acc[ai][bj][m][n] = MFMA16(Bt[n][k], At[m][k], acc[ai][bj][m][n]); __builtin_amdgcn_s_setprio(0); } while (0)
; #define G_WAIT_V(n) asm volatile("s_waitcnt vmcnt(" #n ")" ::: "memory")
; #define G_BAR __builtin_amdgcn_s_barrier()
; template <class Epi>
; __device__ __forceinline__ void gemm_phase(LAS unsigned char* lds, const bf16_t* Ag, const bf16_t* Btg, const int K, const int nM, const int nN, const Epi& E) {
;     ...
;             G_STAGE(G_SB(1, 1), b3 + hstep);
;             G_WAIT_V(6); G_BAR; G_MMA(1, 1, At, B1); G_BAR;
;         }
.LrotX_153:
	s_waitcnt vmcnt(10)
	s_barrier
	v_mfma_f32_16x16x32_bf16 v[60:63], v[232:235], v[160:163], v[60:63]
	v_mfma_f32_16x16x32_bf16 v[56:59], v[240:243], v[160:163], v[56:59]
	v_mfma_f32_16x16x32_bf16 v[44:47], v[232:235], v[168:171], v[44:47]
	v_mfma_f32_16x16x32_bf16 v[40:43], v[240:243], v[168:171], v[40:43]
	v_mfma_f32_16x16x32_bf16 v[28:31], v[232:235], v[180:183], v[28:31]
	v_mfma_f32_16x16x32_bf16 v[24:27], v[240:243], v[180:183], v[24:27]
	v_mfma_f32_16x16x32_bf16 v[12:15], v[232:235], v[188:191], v[12:15]
	v_mfma_f32_16x16x32_bf16 v[8:11], v[240:243], v[188:191], v[8:11]
	v_mfma_f32_16x16x32_bf16 v[60:63], v[236:239], v[164:167], v[60:63]
	v_mfma_f32_16x16x32_bf16 v[56:59], v[244:247], v[164:167], v[56:59]
	v_mfma_f32_16x16x32_bf16 v[44:47], v[236:239], v[172:175], v[44:47]
	v_mfma_f32_16x16x32_bf16 v[40:43], v[244:247], v[172:175], v[40:43]
	v_mfma_f32_16x16x32_bf16 v[28:31], v[236:239], v[184:187], v[28:31]
	v_mfma_f32_16x16x32_bf16 v[24:27], v[244:247], v[184:187], v[24:27]
	v_mfma_f32_16x16x32_bf16 v[12:15], v[236:239], v[192:195], v[12:15]
	v_mfma_f32_16x16x32_bf16 v[8:11], v[244:247], v[192:195], v[8:11]
	s_cmp_gt_u32 s42, 13
	s_barrier
	s_cbranch_scc1 .LBB0_157
	s_cmp_lg_u32 s42, 12
	s_cbranch_scc1 .LmainW_153

; #define G_STAGE(bufoff, gbase) do { _Pragma("unroll") for (int _i = 0; _i < 2; ++_i) \
;         __builtin_amdgcn_global_load_lds((const unsigned*)((const char*)(gbase) + voff[_i]), (LAS unsigned*)(lds + (bufoff) + ldsw + _i * 8192), 16, 0, 0); } while (0)
; #define G_LDA(dst, b, h) do { _Pragma("unroll") for (int m = 0; m < 4; ++m) _Pragma("unroll") for (int k = 0; k < 2; ++k) dst[m][k] = *(const LAS bf16x8*)(lds + G_SA(b, h) + aoff + m * 2048 + k * 1024); } while (0)
; #define G_LDB(dst, b, h) do { _Pragma("unroll") for (int n = 0; n < 2; ++n) _Pragma("unroll") for (int k = 0; k < 2; ++k) dst[n][k] = *(const LAS bf16x8*)(lds + G_SB(b, h) + boff + n * 2048 + k * 1024); } while (0)
; #define G_MMA(ai, bj, At, Bt) do { __builtin_amdgcn_s_setprio(1); _Pragma("unroll") for (int m = 0; m < 4; ++m) _Pragma("unroll") for (int n = 0; n < 2; ++n) _Pragma("unroll") for (int k = 0; k < 2; ++k) \
;         acc[ai][bj][m][n] = MFMA16(Bt[n][k], At[m][k], acc[ai][bj][m][n]); __builtin_amdgcn_s_setprio(0); } while (0)
; #define G_WAIT_V(n) asm volatile("s_waitcnt vmcnt(" #n ")" ::: "memory")
; #define G_WAIT_L(n) asm volatile("s_waitcnt lgkmcnt(" #n ")" ::: "memory")
; #define G_BAR __builtin_amdgcn_s_barrier()
; #define G_SCHED __builtin_amdgcn_sched_barrier(0)
; template <class Epi>
; __device__ __forceinline__ void gemm_phase(LAS unsigned char* lds, const bf16_t* Ag, const bf16_t* Btg, const int K, const int nM, const int nN, const Epi& E) {
;     ...
;             G_LDB(B0, 0, 0); G_SCHED; G_LDA(At, 0, 0); G_STAGE(G_SA(1, 1), a1 + hstep);
;             G_WAIT_L(8); G_BAR; G_WAIT_L(0); G_MMA(0, 0, At, B0); G_BAR; G_SCHED;
;             G_LDB(B1, 0, 1); G_STAGE(G_SB(0, 0), b2);
;             G_BAR; G_WAIT_L(0); G_MMA(0, 1, At, B1); G_BAR;
;             G_LDA(At, 0, 1); G_STAGE(G_SA(0, 0), a2);
;             G_BAR; G_WAIT_L(0); G_MMA(1, 0, At, B0); G_BAR; G_SCHED;
;             G_STAGE(G_SB(0, 1), b2 + hstep);
;             G_WAIT_V(6); G_BAR; G_MMA(1, 1, At, B1); G_BAR;
.LmainW_744:
	ds_read_b128 v[140:143], v217
	ds_read_b128 v[144:147], v217 offset:1024
	ds_read_b128 v[148:151], v217 offset:2048
	ds_read_b128 v[152:155], v217 offset:3072
	s_add_i32 m0, s66, 0xc000
	ds_read_b128 v[156:159], v174
	ds_read_b128 v[160:163], v174 offset:1024
	ds_read_b128 v[180:183], v174 offset:2048
	ds_read_b128 v[184:187], v174 offset:3072
	ds_read_b128 v[188:191], v174 offset:4096
	ds_read_b128 v[192:195], v174 offset:5120
	ds_read_b128 v[222:225], v174 offset:6144
	global_load_lds_dwordx4 v138, s[56:57]
	s_add_i32 m0, s66, 0xe000
	ds_read_b128 v[226:229], v174 offset:7168
	global_load_lds_dwordx4 v136, s[56:57]
	s_waitcnt vmcnt(10) lgkmcnt(8)
	s_barrier
	s_waitcnt lgkmcnt(0)
	s_waitcnt lgkmcnt(0)
	v_mfma_f32_16x16x32_bf16 v[132:135], v[140:143], v[156:159], v[132:135]
	v_mfma_f32_16x16x32_bf16 v[128:131], v[148:151], v[156:159], v[128:131]
	v_mfma_f32_16x16x32_bf16 v[116:119], v[140:143], v[180:183], v[116:119]
	v_mfma_f32_16x16x32_bf16 v[112:115], v[148:151], v[180:183], v[112:115]
	v_mfma_f32_16x16x32_bf16 v[100:103], v[140:143], v[188:191], v[100:103]
	v_mfma_f32_16x16x32_bf16 v[96:99], v[148:151], v[188:191], v[96:99]
	v_mfma_f32_16x16x32_bf16 v[84:87], v[140:143], v[222:225], v[84:87]
	v_mfma_f32_16x16x32_bf16 v[80:83], v[148:151], v[222:225], v[80:83]
	v_mfma_f32_16x16x32_bf16 v[132:135], v[144:147], v[160:163], v[132:135]
	v_mfma_f32_16x16x32_bf16 v[128:131], v[152:155], v[160:163], v[128:131]
	v_mfma_f32_16x16x32_bf16 v[116:119], v[144:147], v[184:187], v[116:119]
	v_mfma_f32_16x16x32_bf16 v[112:115], v[152:155], v[184:187], v[112:115]
	v_mfma_f32_16x16x32_bf16 v[100:103], v[144:147], v[192:195], v[100:103]
	v_mfma_f32_16x16x32_bf16 v[96:99], v[152:155], v[192:195], v[96:99]
	v_mfma_f32_16x16x32_bf16 v[84:87], v[144:147], v[226:229], v[84:87]
	v_mfma_f32_16x16x32_bf16 v[80:83], v[152:155], v[226:229], v[80:83]
	s_barrier
	s_add_i32 m0, s65, 0x10000
	ds_read_b128 v[230:233], v217 offset:16384
	ds_read_b128 v[234:237], v217 offset:17408
	ds_read_b128 v[238:241], v217 offset:18432
	global_load_lds_dwordx4 v0, s[60:61]
	s_add_i32 m0, s65, 0x12000
	ds_read_b128 v[242:245], v217 offset:19456
	global_load_lds_dwordx4 v2, s[60:61]
	s_waitcnt vmcnt(10)
	s_barrier
	s_waitcnt lgkmcnt(0)
	s_waitcnt lgkmcnt(0)
	v_mfma_f32_16x16x32_bf16 v[124:127], v[230:233], v[156:159], v[124:127]
	v_mfma_f32_16x16x32_bf16 v[120:123], v[238:241], v[156:159], v[120:123]
	v_mfma_f32_16x16x32_bf16 v[108:111], v[230:233], v[180:183], v[108:111]
	v_mfma_f32_16x16x32_bf16 v[104:107], v[238:241], v[180:183], v[104:107]
	v_mfma_f32_16x16x32_bf16 v[92:95], v[230:233], v[188:191], v[92:95]
	v_mfma_f32_16x16x32_bf16 v[88:91], v[238:241], v[188:191], v[88:91]
	v_mfma_f32_16x16x32_bf16 v[76:79], v[230:233], v[222:225], v[76:79]
	v_mfma_f32_16x16x32_bf16 v[72:75], v[238:241], v[222:225], v[72:75]
	v_mfma_f32_16x16x32_bf16 v[124:127], v[234:237], v[160:163], v[124:127]
	v_mfma_f32_16x16x32_bf16 v[120:123], v[242:245], v[160:163], v[120:123]
	v_mfma_f32_16x16x32_bf16 v[108:111], v[234:237], v[184:187], v[108:111]
	v_mfma_f32_16x16x32_bf16 v[104:107], v[242:245], v[184:187], v[104:107]
	v_mfma_f32_16x16x32_bf16 v[92:95], v[234:237], v[192:195], v[92:95]
	v_mfma_f32_16x16x32_bf16 v[88:91], v[242:245], v[192:195], v[88:91]
	v_mfma_f32_16x16x32_bf16 v[76:79], v[234:237], v[226:229], v[76:79]
	v_mfma_f32_16x16x32_bf16 v[72:75], v[242:245], v[226:229], v[72:75]
	s_mov_b32 m0, s66
	s_barrier
	ds_read_b128 v[156:159], v174 offset:16384
	ds_read_b128 v[160:163], v174 offset:17408
	ds_read_b128 v[180:183], v174 offset:18432
	ds_read_b128 v[184:187], v174 offset:19456
	ds_read_b128 v[188:191], v174 offset:20480
	ds_read_b128 v[192:195], v174 offset:21504
	ds_read_b128 v[222:225], v174 offset:22528
	global_load_lds_dwordx4 v0, s[62:63]
	s_mov_b32 m0, s67
	ds_read_b128 v[226:229], v174 offset:23552
	global_load_lds_dwordx4 v2, s[62:63]
	s_barrier
	s_waitcnt lgkmcnt(0)
	s_waitcnt lgkmcnt(0)
	v_mfma_f32_16x16x32_bf16 v[68:71], v[140:143], v[156:159], v[68:71]
	v_mfma_f32_16x16x32_bf16 v[64:67], v[148:151], v[156:159], v[64:67]
	v_mfma_f32_16x16x32_bf16 v[52:55], v[140:143], v[180:183], v[52:55]
	v_mfma_f32_16x16x32_bf16 v[48:51], v[148:151], v[180:183], v[48:51]
	v_mfma_f32_16x16x32_bf16 v[36:39], v[140:143], v[188:191], v[36:39]
	v_mfma_f32_16x16x32_bf16 v[32:35], v[148:151], v[188:191], v[32:35]
	v_mfma_f32_16x16x32_bf16 v[20:23], v[140:143], v[222:225], v[20:23]
	v_mfma_f32_16x16x32_bf16 v[16:19], v[148:151], v[222:225], v[16:19]
	v_mfma_f32_16x16x32_bf16 v[68:71], v[144:147], v[160:163], v[68:71]
	v_mfma_f32_16x16x32_bf16 v[64:67], v[152:155], v[160:163], v[64:67]
	v_mfma_f32_16x16x32_bf16 v[52:55], v[144:147], v[184:187], v[52:55]
	v_mfma_f32_16x16x32_bf16 v[48:51], v[152:155], v[184:187], v[48:51]
	v_mfma_f32_16x16x32_bf16 v[36:39], v[144:147], v[192:195], v[36:39]
	v_mfma_f32_16x16x32_bf16 v[32:35], v[152:155], v[192:195], v[32:35]
	v_mfma_f32_16x16x32_bf16 v[20:23], v[144:147], v[226:229], v[20:23]
	v_mfma_f32_16x16x32_bf16 v[16:19], v[152:155], v[226:229], v[16:19]
	s_barrier
	s_add_i32 m0, s65, 0x14000
	s_add_u32 s56, s60, 0x100000
	s_addc_u32 s57, s61, 0
	global_load_lds_dwordx4 v0, s[56:57]
	s_add_i32 m0, s65, 0x16000
	s_add_u32 s98, s62, 0x100000
	s_addc_u32 s99, s63, 0
	global_load_lds_dwordx4 v2, s[56:57]
	s_waitcnt vmcnt(10)
	s_barrier
; #define G_STAGE(bufoff, gbase) do { _Pragma("unroll") for (int _i = 0; _i < 2; ++_i) \
;         __builtin_amdgcn_global_load_lds((const unsigned*)((const char*)(gbase) + voff[_i]), (LAS unsigned*)(lds + (bufoff) + ldsw + _i * 8192), 16, 0, 0); } while (0)
; #define G_LDA(dst, b, h) do { _Pragma("unroll") for (int m = 0; m < 4; ++m) _Pragma("unroll") for (int k = 0; k < 2; ++k) dst[m][k] = *(const LAS bf16x8*)(lds + G_SA(b, h) + aoff + m * 2048 + k * 1024); } while (0)
; #define G_LDB(dst, b, h) do { _Pragma("unroll") for (int n = 0; n < 2; ++n) _Pragma("unroll") for (int k = 0; k < 2; ++k) dst[n][k] = *(const LAS bf16x8*)(lds + G_SB(b, h) + boff + n * 2048 + k * 1024); } while (0)
; #define G_MMA(ai, bj, At, Bt) do { __builtin_amdgcn_s_setprio(1); _Pragma("unroll") for (int m = 0; m < 4; ++m) _Pragma("unroll") for (int n = 0; n < 2; ++n) _Pragma("unroll") for (int k = 0; k < 2; ++k) \
;         acc[ai][bj][m][n] = MFMA16(Bt[n][k], At[m][k], acc[ai][bj][m][n]); __builtin_amdgcn_s_setprio(0); } while (0)
; #define G_WAIT_V(n) asm volatile("s_waitcnt vmcnt(" #n ")" ::: "memory")
; #define G_WAIT_L(n) asm volatile("s_waitcnt lgkmcnt(" #n ")" ::: "memory")
; #define G_BAR __builtin_amdgcn_s_barrier()
; #define G_SCHED __builtin_amdgcn_sched_barrier(0)
; template <class Epi>
; __device__ __forceinline__ void gemm_phase(LAS unsigned char* lds, const bf16_t* Ag, const bf16_t* Btg, const int K, const int nM, const int nN, const Epi& E) {
;     ...
;             const char* a1 = cA + (size_t)(t + 1) * kstep;
;             const char* a2 = last ? nA : cA + (size_t)(t + 2) * kstep; const char* b2 = last ? nB : cB + (size_t)(t + 2) * kstep;
;             const char* a3 = a2 + kstep; const char* b3 = b2 + kstep;
;     ...
;             G_WAIT_V(6); G_BAR; G_MMA(1, 1, At, B1); G_BAR;
;             G_LDB(B0, 1, 0); G_SCHED; G_LDA(At, 1, 0); G_STAGE(G_SA(0, 1), a2 + hstep);
;             G_WAIT_L(8); G_BAR; G_WAIT_L(0); G_MMA(0, 0, At, B0); G_BAR; G_SCHED;
;             G_LDB(B1, 1, 1); G_STAGE(G_SB(1, 0), b3);
;             G_BAR; G_WAIT_L(0); G_MMA(0, 1, At, B1); G_BAR;
;             G_LDA(At, 1, 1); G_STAGE(G_SA(1, 0), a3);
;             G_BAR; G_WAIT_L(0); G_MMA(1, 0, At, B0); G_BAR; G_SCHED;
;             G_STAGE(G_SB(1, 1), b3 + hstep);
;             G_WAIT_V(6); G_BAR; G_MMA(1, 1, At, B1); G_BAR;
	v_mfma_f32_16x16x32_bf16 v[60:63], v[230:233], v[156:159], v[60:63]
	v_mfma_f32_16x16x32_bf16 v[56:59], v[238:241], v[156:159], v[56:59]
	v_mfma_f32_16x16x32_bf16 v[44:47], v[230:233], v[180:183], v[44:47]
	v_mfma_f32_16x16x32_bf16 v[40:43], v[238:241], v[180:183], v[40:43]
	v_mfma_f32_16x16x32_bf16 v[28:31], v[230:233], v[188:191], v[28:31]
	v_mfma_f32_16x16x32_bf16 v[24:27], v[238:241], v[188:191], v[24:27]
	v_mfma_f32_16x16x32_bf16 v[12:15], v[230:233], v[222:225], v[12:15]
	v_mfma_f32_16x16x32_bf16 v[8:11], v[238:241], v[222:225], v[8:11]
	v_mfma_f32_16x16x32_bf16 v[60:63], v[234:237], v[160:163], v[60:63]
	v_mfma_f32_16x16x32_bf16 v[56:59], v[242:245], v[160:163], v[56:59]
	v_mfma_f32_16x16x32_bf16 v[44:47], v[234:237], v[184:187], v[44:47]
	v_mfma_f32_16x16x32_bf16 v[40:43], v[242:245], v[184:187], v[40:43]
	v_mfma_f32_16x16x32_bf16 v[28:31], v[234:237], v[192:195], v[28:31]
	v_mfma_f32_16x16x32_bf16 v[24:27], v[242:245], v[192:195], v[24:27]
	v_mfma_f32_16x16x32_bf16 v[12:15], v[234:237], v[226:229], v[12:15]
	v_mfma_f32_16x16x32_bf16 v[8:11], v[242:245], v[226:229], v[8:11]
	s_barrier
	ds_read_b128 v[140:143], v217 offset:32768
	ds_read_b128 v[144:147], v217 offset:33792
	ds_read_b128 v[148:151], v217 offset:34816
	ds_read_b128 v[152:155], v217 offset:35840
	s_mov_b32 m0, s68
	ds_read_b128 v[156:159], v174 offset:32768
	ds_read_b128 v[160:163], v174 offset:33792
	ds_read_b128 v[180:183], v174 offset:34816
	ds_read_b128 v[184:187], v174 offset:35840
	ds_read_b128 v[188:191], v174 offset:36864
	ds_read_b128 v[192:195], v174 offset:37888
	ds_read_b128 v[222:225], v174 offset:38912
	global_load_lds_dwordx4 v0, s[98:99]
	s_mov_b32 m0, s69
	ds_read_b128 v[226:229], v174 offset:39936
	global_load_lds_dwordx4 v2, s[98:99]
	s_waitcnt vmcnt(10) lgkmcnt(8)
	s_barrier
	s_waitcnt lgkmcnt(0)
	s_waitcnt lgkmcnt(0)
	v_mfma_f32_16x16x32_bf16 v[132:135], v[140:143], v[156:159], v[132:135]
	v_mfma_f32_16x16x32_bf16 v[128:131], v[148:151], v[156:159], v[128:131]
	v_mfma_f32_16x16x32_bf16 v[116:119], v[140:143], v[180:183], v[116:119]
	v_mfma_f32_16x16x32_bf16 v[112:115], v[148:151], v[180:183], v[112:115]
	v_mfma_f32_16x16x32_bf16 v[100:103], v[140:143], v[188:191], v[100:103]
	v_mfma_f32_16x16x32_bf16 v[96:99], v[148:151], v[188:191], v[96:99]
	v_mfma_f32_16x16x32_bf16 v[84:87], v[140:143], v[222:225], v[84:87]
	v_mfma_f32_16x16x32_bf16 v[80:83], v[148:151], v[222:225], v[80:83]
	v_mfma_f32_16x16x32_bf16 v[132:135], v[144:147], v[160:163], v[132:135]
	v_mfma_f32_16x16x32_bf16 v[128:131], v[152:155], v[160:163], v[128:131]
	v_mfma_f32_16x16x32_bf16 v[116:119], v[144:147], v[184:187], v[116:119]
	v_mfma_f32_16x16x32_bf16 v[112:115], v[152:155], v[184:187], v[112:115]
	v_mfma_f32_16x16x32_bf16 v[100:103], v[144:147], v[192:195], v[100:103]
	v_mfma_f32_16x16x32_bf16 v[96:99], v[152:155], v[192:195], v[96:99]
	v_mfma_f32_16x16x32_bf16 v[84:87], v[144:147], v[226:229], v[84:87]
	v_mfma_f32_16x16x32_bf16 v[80:83], v[152:155], v[226:229], v[80:83]
	s_barrier
	s_add_i32 m0, s65, 0x18000
	ds_read_b128 v[230:233], v217 offset:49152
	ds_read_b128 v[234:237], v217 offset:50176
	ds_read_b128 v[238:241], v217 offset:51200
	s_add_u32 s98, s60, 0x80
	s_addc_u32 s99, s61, 0
	global_load_lds_dwordx4 v0, s[98:99]
	s_add_i32 m0, s65, 0x1a000
	ds_read_b128 v[242:245], v217 offset:52224
	global_load_lds_dwordx4 v2, s[98:99]
	s_waitcnt vmcnt(10)
	s_barrier
	s_waitcnt lgkmcnt(0)
	s_waitcnt lgkmcnt(0)
	v_mfma_f32_16x16x32_bf16 v[124:127], v[230:233], v[156:159], v[124:127]
	v_mfma_f32_16x16x32_bf16 v[120:123], v[238:241], v[156:159], v[120:123]
	v_mfma_f32_16x16x32_bf16 v[108:111], v[230:233], v[180:183], v[108:111]
	v_mfma_f32_16x16x32_bf16 v[104:107], v[238:241], v[180:183], v[104:107]
	v_mfma_f32_16x16x32_bf16 v[92:95], v[230:233], v[188:191], v[92:95]
	v_mfma_f32_16x16x32_bf16 v[88:91], v[238:241], v[188:191], v[88:91]
	v_mfma_f32_16x16x32_bf16 v[76:79], v[230:233], v[222:225], v[76:79]
	v_mfma_f32_16x16x32_bf16 v[72:75], v[238:241], v[222:225], v[72:75]
	v_mfma_f32_16x16x32_bf16 v[124:127], v[234:237], v[160:163], v[124:127]
	v_mfma_f32_16x16x32_bf16 v[120:123], v[242:245], v[160:163], v[120:123]
	v_mfma_f32_16x16x32_bf16 v[108:111], v[234:237], v[184:187], v[108:111]
	v_mfma_f32_16x16x32_bf16 v[104:107], v[242:245], v[184:187], v[104:107]
	v_mfma_f32_16x16x32_bf16 v[92:95], v[234:237], v[192:195], v[92:95]
	v_mfma_f32_16x16x32_bf16 v[88:91], v[242:245], v[192:195], v[88:91]
	v_mfma_f32_16x16x32_bf16 v[76:79], v[234:237], v[226:229], v[76:79]
	v_mfma_f32_16x16x32_bf16 v[72:75], v[242:245], v[226:229], v[72:75]
	s_mov_b32 m0, s70
	s_barrier
	ds_read_b128 v[156:159], v174 offset:49152
	ds_read_b128 v[160:163], v174 offset:50176
	ds_read_b128 v[180:183], v174 offset:51200
	ds_read_b128 v[184:187], v174 offset:52224
	ds_read_b128 v[188:191], v174 offset:53248
	ds_read_b128 v[192:195], v174 offset:54272
	ds_read_b128 v[222:225], v174 offset:55296
	s_add_u32 s98, s62, 0x80
	s_addc_u32 s99, s63, 0
	global_load_lds_dwordx4 v0, s[98:99]
	s_mov_b32 m0, s71
	ds_read_b128 v[226:229], v174 offset:56320
	global_load_lds_dwordx4 v2, s[98:99]
	s_barrier
	s_waitcnt lgkmcnt(0)
	s_waitcnt lgkmcnt(0)
	v_mfma_f32_16x16x32_bf16 v[68:71], v[140:143], v[156:159], v[68:71]
	v_mfma_f32_16x16x32_bf16 v[64:67], v[148:151], v[156:159], v[64:67]
	v_mfma_f32_16x16x32_bf16 v[52:55], v[140:143], v[180:183], v[52:55]
	v_mfma_f32_16x16x32_bf16 v[48:51], v[148:151], v[180:183], v[48:51]
	v_mfma_f32_16x16x32_bf16 v[36:39], v[140:143], v[188:191], v[36:39]
	v_mfma_f32_16x16x32_bf16 v[32:35], v[148:151], v[188:191], v[32:35]
	v_mfma_f32_16x16x32_bf16 v[20:23], v[140:143], v[222:225], v[20:23]
	v_mfma_f32_16x16x32_bf16 v[16:19], v[148:151], v[222:225], v[16:19]
	v_mfma_f32_16x16x32_bf16 v[68:71], v[144:147], v[160:163], v[68:71]
	v_mfma_f32_16x16x32_bf16 v[64:67], v[152:155], v[160:163], v[64:67]
	v_mfma_f32_16x16x32_bf16 v[52:55], v[144:147], v[184:187], v[52:55]
	v_mfma_f32_16x16x32_bf16 v[48:51], v[152:155], v[184:187], v[48:51]
	v_mfma_f32_16x16x32_bf16 v[36:39], v[144:147], v[192:195], v[36:39]
	v_mfma_f32_16x16x32_bf16 v[32:35], v[152:155], v[192:195], v[32:35]
	v_mfma_f32_16x16x32_bf16 v[20:23], v[144:147], v[226:229], v[20:23]
	v_mfma_f32_16x16x32_bf16 v[16:19], v[152:155], v[226:229], v[16:19]
	s_barrier
	s_add_i32 m0, s65, 0x1c000
	s_add_u32 s56, s60, 0x100080
	s_addc_u32 s57, s61, 0
	global_load_lds_dwordx4 v0, s[56:57]
	s_add_i32 m0, s65, 0x1e000
	s_add_i32 s79, s79, 2
	global_load_lds_dwordx4 v2, s[56:57]
	s_add_u32 s77, s77, 0x100
	s_addc_u32 s78, s78, 0
	s_mov_b64 s[56:57], s[58:59]
	s_cmp_gt_u32 s79, 61
	s_cbranch_scc1 .LrotX_744
	s_cmp_lg_u32 s79, 60
	s_cselect_b64 s[60:61], -1, 0
	s_add_u32 s58, s56, 0x100
	s_addc_u32 s59, s57, 0
	s_and_b64 s[60:61], s[60:61], exec
	s_cselect_b32 s63, s59, s47
	s_cselect_b32 s62, s58, s46
	s_cselect_b32 s61, s78, s15
	s_cselect_b32 s60, s77, s49
; #define G_STAGE(bufoff, gbase) do { _Pragma("unroll") for (int _i = 0; _i < 2; ++_i) \
;         __builtin_amdgcn_global_load_lds((const unsigned*)((const char*)(gbase) + voff[_i]), (LAS unsigned*)(lds + (bufoff) + ldsw + _i * 8192), 16, 0, 0); } while (0)
; #define G_MMA(ai, bj, At, Bt) do { __builtin_amdgcn_s_setprio(1); _Pragma("unroll") for (int m = 0; m < 4; ++m) _Pragma("unroll") for (int n = 0; n < 2; ++n) _Pragma("unroll") for (int k = 0; k < 2; ++k) \
;         acc[ai][bj][m][n] = MFMA16(Bt[n][k], At[m][k], acc[ai][bj][m][n]); __builtin_amdgcn_s_setprio(0); } while (0)
; #define G_WAIT_V(n) asm volatile("s_waitcnt vmcnt(" #n ")" ::: "memory")
; #define G_BAR __builtin_amdgcn_s_barrier()
; template <class Epi>
; __device__ __forceinline__ void gemm_phase(LAS unsigned char* lds, const bf16_t* Ag, const bf16_t* Btg, const int K, const int nM, const int nN, const Epi& E) {
;     ...
;             G_STAGE(G_SB(1, 1), b3 + hstep);
;             G_WAIT_V(6); G_BAR; G_MMA(1, 1, At, B1); G_BAR;
;         }
.LrotX_744:
	s_waitcnt vmcnt(10)
	s_barrier
	v_mfma_f32_16x16x32_bf16 v[60:63], v[230:233], v[156:159], v[60:63]
	v_mfma_f32_16x16x32_bf16 v[56:59], v[238:241], v[156:159], v[56:59]
	v_mfma_f32_16x16x32_bf16 v[44:47], v[230:233], v[180:183], v[44:47]
	v_mfma_f32_16x16x32_bf16 v[40:43], v[238:241], v[180:183], v[40:43]
	v_mfma_f32_16x16x32_bf16 v[28:31], v[230:233], v[188:191], v[28:31]
	v_mfma_f32_16x16x32_bf16 v[24:27], v[238:241], v[188:191], v[24:27]
	v_mfma_f32_16x16x32_bf16 v[12:15], v[230:233], v[222:225], v[12:15]
	v_mfma_f32_16x16x32_bf16 v[8:11], v[238:241], v[222:225], v[8:11]
	v_mfma_f32_16x16x32_bf16 v[60:63], v[234:237], v[160:163], v[60:63]
	v_mfma_f32_16x16x32_bf16 v[56:59], v[242:245], v[160:163], v[56:59]
	v_mfma_f32_16x16x32_bf16 v[44:47], v[234:237], v[184:187], v[44:47]
	v_mfma_f32_16x16x32_bf16 v[40:43], v[242:245], v[184:187], v[40:43]
	v_mfma_f32_16x16x32_bf16 v[28:31], v[234:237], v[192:195], v[28:31]
	v_mfma_f32_16x16x32_bf16 v[24:27], v[242:245], v[192:195], v[24:27]
	v_mfma_f32_16x16x32_bf16 v[12:15], v[234:237], v[226:229], v[12:15]
	v_mfma_f32_16x16x32_bf16 v[8:11], v[242:245], v[226:229], v[8:11]
	s_cmp_gt_u32 s79, 61
	s_barrier
	s_cbranch_scc1 .LBB0_748
	s_cmp_lg_u32 s79, 60
	s_cbranch_scc1 .LmainW_744

; #define G_STAGE(bufoff, gbase) do { _Pragma("unroll") for (int _i = 0; _i < 2; ++_i) \
;         __builtin_amdgcn_global_load_lds((const unsigned*)((const char*)(gbase) + voff[_i]), (LAS unsigned*)(lds + (bufoff) + ldsw + _i * 8192), 16, 0, 0); } while (0)
; #define G_LDA(dst, b, h) do { _Pragma("unroll") for (int m = 0; m < 4; ++m) _Pragma("unroll") for (int k = 0; k < 2; ++k) dst[m][k] = *(const LAS bf16x8*)(lds + G_SA(b, h) + aoff + m * 2048 + k * 1024); } while (0)
; #define G_LDB(dst, b, h) do { _Pragma("unroll") for (int n = 0; n < 2; ++n) _Pragma("unroll") for (int k = 0; k < 2; ++k) dst[n][k] = *(const LAS bf16x8*)(lds + G_SB(b, h) + boff + n * 2048 + k * 1024); } while (0)
; #define G_MMA(ai, bj, At, Bt) do { __builtin_amdgcn_s_setprio(1); _Pragma("unroll") for (int m = 0; m < 4; ++m) _Pragma("unroll") for (int n = 0; n < 2; ++n) _Pragma("unroll") for (int k = 0; k < 2; ++k) \
;         acc[ai][bj][m][n] = MFMA16(Bt[n][k], At[m][k], acc[ai][bj][m][n]); __builtin_amdgcn_s_setprio(0); } while (0)
; #define G_WAIT_V(n) asm volatile("s_waitcnt vmcnt(" #n ")" ::: "memory")
; #define G_WAIT_L(n) asm volatile("s_waitcnt lgkmcnt(" #n ")" ::: "memory")
; #define G_BAR __builtin_amdgcn_s_barrier()
; #define G_SCHED __builtin_amdgcn_sched_barrier(0)
; template <class Epi>
; __device__ __forceinline__ void gemm_phase(LAS unsigned char* lds, const bf16_t* Ag, const bf16_t* Btg, const int K, const int nM, const int nN, const Epi& E) {
;     ...
;             G_LDB(B0, 0, 0); G_SCHED; G_LDA(At, 0, 0); G_STAGE(G_SA(1, 1), a1 + hstep);
;             G_WAIT_L(8); G_BAR; G_WAIT_L(0); G_MMA(0, 0, At, B0); G_BAR; G_SCHED;
;             G_LDB(B1, 0, 1); G_STAGE(G_SB(0, 0), b2);
;             G_BAR; G_WAIT_L(0); G_MMA(0, 1, At, B1); G_BAR;
;             G_LDA(At, 0, 1); G_STAGE(G_SA(0, 0), a2);
;             G_BAR; G_WAIT_L(0); G_MMA(1, 0, At, B0); G_BAR; G_SCHED;
;             G_STAGE(G_SB(0, 1), b2 + hstep);
;             G_WAIT_V(6); G_BAR; G_MMA(1, 1, At, B1); G_BAR;
.LmainW_848:
	ds_read_b128 v[130:133], v217
	ds_read_b128 v[134:137], v217 offset:1024
	ds_read_b128 v[144:147], v217 offset:2048
	ds_read_b128 v[148:151], v217 offset:3072
	s_add_i32 m0, s60, 0xc000
	ds_read_b128 v[156:159], v222
	ds_read_b128 v[160:163], v222 offset:1024
	ds_read_b128 v[164:167], v222 offset:2048
	ds_read_b128 v[180:183], v222 offset:3072
	ds_read_b128 v[184:187], v222 offset:4096
	ds_read_b128 v[224:227], v222 offset:5120
	ds_read_b128 v[228:231], v222 offset:6144
	global_load_lds_dwordx4 v170, s[50:51]
	s_add_i32 m0, s60, 0xe000
	ds_read_b128 v[232:235], v222 offset:7168
	global_load_lds_dwordx4 v168, s[50:51]
	s_waitcnt vmcnt(10) lgkmcnt(8)
	s_barrier
	s_waitcnt lgkmcnt(0)
	s_waitcnt lgkmcnt(0)
	v_mfma_f32_16x16x32_bf16 v[152:155], v[130:133], v[156:159], v[152:155]
	v_mfma_f32_16x16x32_bf16 v[138:141], v[144:147], v[156:159], v[140:143]
	v_mfma_f32_16x16x32_bf16 v[116:119], v[130:133], v[164:167], v[116:119]
	v_mfma_f32_16x16x32_bf16 v[112:115], v[144:147], v[164:167], v[112:115]
	v_mfma_f32_16x16x32_bf16 v[100:103], v[130:133], v[184:187], v[100:103]
	v_mfma_f32_16x16x32_bf16 v[96:99], v[144:147], v[184:187], v[96:99]
	v_mfma_f32_16x16x32_bf16 v[84:87], v[130:133], v[228:231], v[84:87]
	v_mfma_f32_16x16x32_bf16 v[80:83], v[144:147], v[228:231], v[80:83]
	v_mfma_f32_16x16x32_bf16 v[152:155], v[134:137], v[160:163], v[152:155]
	v_mfma_f32_16x16x32_bf16 v[138:141], v[148:151], v[160:163], v[138:141]
	v_mfma_f32_16x16x32_bf16 v[116:119], v[134:137], v[180:183], v[116:119]
	v_mfma_f32_16x16x32_bf16 v[112:115], v[148:151], v[180:183], v[112:115]
	v_mfma_f32_16x16x32_bf16 v[100:103], v[134:137], v[224:227], v[100:103]
	v_mfma_f32_16x16x32_bf16 v[96:99], v[148:151], v[224:227], v[96:99]
	v_mfma_f32_16x16x32_bf16 v[84:87], v[134:137], v[232:235], v[84:87]
	v_mfma_f32_16x16x32_bf16 v[80:83], v[148:151], v[232:235], v[80:83]
	s_barrier
	s_add_i32 s73, 0, 0x14000
	s_add_i32 m0, s59, 0x10000
	ds_read_b128 v[236:239], v217 offset:16384
	ds_read_b128 v[240:243], v217 offset:17408
	ds_read_b128 v[244:247], v217 offset:18432
	global_load_lds_dwordx4 v0, s[52:53]
	s_add_i32 m0, s59, 0x12000
	ds_read_b128 v[248:251], v217 offset:19456
	global_load_lds_dwordx4 v2, s[52:53]
	s_waitcnt vmcnt(10)
	s_barrier
	s_waitcnt lgkmcnt(0)
	s_waitcnt lgkmcnt(0)
	v_mfma_f32_16x16x32_bf16 v[124:127], v[236:239], v[156:159], v[124:127]
	v_mfma_f32_16x16x32_bf16 v[120:123], v[244:247], v[156:159], v[120:123]
	v_mfma_f32_16x16x32_bf16 v[108:111], v[236:239], v[164:167], v[108:111]
	v_mfma_f32_16x16x32_bf16 v[104:107], v[244:247], v[164:167], v[104:107]
	v_mfma_f32_16x16x32_bf16 v[92:95], v[236:239], v[184:187], v[92:95]
	v_mfma_f32_16x16x32_bf16 v[88:91], v[244:247], v[184:187], v[88:91]
	v_mfma_f32_16x16x32_bf16 v[76:79], v[236:239], v[228:231], v[76:79]
	v_mfma_f32_16x16x32_bf16 v[72:75], v[244:247], v[228:231], v[72:75]
	v_mfma_f32_16x16x32_bf16 v[124:127], v[240:243], v[160:163], v[124:127]
	v_mfma_f32_16x16x32_bf16 v[120:123], v[248:251], v[160:163], v[120:123]
	v_mfma_f32_16x16x32_bf16 v[108:111], v[240:243], v[180:183], v[108:111]
	v_mfma_f32_16x16x32_bf16 v[104:107], v[248:251], v[180:183], v[104:107]
	v_mfma_f32_16x16x32_bf16 v[92:95], v[240:243], v[224:227], v[92:95]
	v_mfma_f32_16x16x32_bf16 v[88:91], v[248:251], v[224:227], v[88:91]
	v_mfma_f32_16x16x32_bf16 v[76:79], v[240:243], v[232:235], v[76:79]
	v_mfma_f32_16x16x32_bf16 v[72:75], v[248:251], v[232:235], v[72:75]
	s_mov_b32 m0, s60
	s_add_u32 s76, s54, 0x80
	s_addc_u32 s77, s55, 0
	s_barrier
	ds_read_b128 v[156:159], v222 offset:16384
	ds_read_b128 v[160:163], v222 offset:17408
	ds_read_b128 v[164:167], v222 offset:18432
	ds_read_b128 v[180:183], v222 offset:19456
	ds_read_b128 v[184:187], v222 offset:20480
	ds_read_b128 v[224:227], v222 offset:21504
	ds_read_b128 v[228:231], v222 offset:22528
	ds_read_b128 v[232:235], v222 offset:23552
	global_load_lds_dwordx4 v0, s[54:55]
	s_add_u32 s76, s54, 0x80
	s_mov_b32 m0, s61
	s_addc_u32 s77, s55, 0
	global_load_lds_dwordx4 v2, s[54:55]
	s_barrier
	s_waitcnt lgkmcnt(0)
	s_waitcnt lgkmcnt(0)
	v_mfma_f32_16x16x32_bf16 v[60:63], v[130:133], v[156:159], v[60:63]
	v_mfma_f32_16x16x32_bf16 v[56:59], v[144:147], v[156:159], v[56:59]
	v_mfma_f32_16x16x32_bf16 v[44:47], v[130:133], v[164:167], v[44:47]
	v_mfma_f32_16x16x32_bf16 v[40:43], v[144:147], v[164:167], v[40:43]
	v_mfma_f32_16x16x32_bf16 v[28:31], v[130:133], v[184:187], v[28:31]
	v_mfma_f32_16x16x32_bf16 v[24:27], v[144:147], v[184:187], v[24:27]
	v_mfma_f32_16x16x32_bf16 v[12:15], v[130:133], v[228:231], v[12:15]
	v_mfma_f32_16x16x32_bf16 v[8:11], v[144:147], v[228:231], v[8:11]
	v_mfma_f32_16x16x32_bf16 v[60:63], v[134:137], v[160:163], v[60:63]
	v_mfma_f32_16x16x32_bf16 v[56:59], v[148:151], v[160:163], v[56:59]
	v_mfma_f32_16x16x32_bf16 v[44:47], v[134:137], v[180:183], v[44:47]
	v_mfma_f32_16x16x32_bf16 v[40:43], v[148:151], v[180:183], v[40:43]
	v_mfma_f32_16x16x32_bf16 v[28:31], v[134:137], v[224:227], v[28:31]
	v_mfma_f32_16x16x32_bf16 v[24:27], v[148:151], v[224:227], v[24:27]
	v_mfma_f32_16x16x32_bf16 v[12:15], v[134:137], v[232:235], v[12:15]
	v_mfma_f32_16x16x32_bf16 v[8:11], v[148:151], v[232:235], v[8:11]
	s_barrier
	s_add_i32 m0, s59, 0x14000
	s_add_u32 s74, s52, 0x40000
	s_addc_u32 s75, s53, 0
	global_load_lds_dwordx4 v0, s[74:75]
	s_add_i32 m0, s59, 0x16000
	s_add_u32 s54, s54, 0x40000
	s_addc_u32 s55, s55, 0
	global_load_lds_dwordx4 v2, s[74:75]
	s_waitcnt vmcnt(10)
	s_barrier
; #define G_STAGE(bufoff, gbase) do { _Pragma("unroll") for (int _i = 0; _i < 2; ++_i) \
;         __builtin_amdgcn_global_load_lds((const unsigned*)((const char*)(gbase) + voff[_i]), (LAS unsigned*)(lds + (bufoff) + ldsw + _i * 8192), 16, 0, 0); } while (0)
; #define G_LDA(dst, b, h) do { _Pragma("unroll") for (int m = 0; m < 4; ++m) _Pragma("unroll") for (int k = 0; k < 2; ++k) dst[m][k] = *(const LAS bf16x8*)(lds + G_SA(b, h) + aoff + m * 2048 + k * 1024); } while (0)
; #define G_LDB(dst, b, h) do { _Pragma("unroll") for (int n = 0; n < 2; ++n) _Pragma("unroll") for (int k = 0; k < 2; ++k) dst[n][k] = *(const LAS bf16x8*)(lds + G_SB(b, h) + boff + n * 2048 + k * 1024); } while (0)
; #define G_MMA(ai, bj, At, Bt) do { __builtin_amdgcn_s_setprio(1); _Pragma("unroll") for (int m = 0; m < 4; ++m) _Pragma("unroll") for (int n = 0; n < 2; ++n) _Pragma("unroll") for (int k = 0; k < 2; ++k) \
;         acc[ai][bj][m][n] = MFMA16(Bt[n][k], At[m][k], acc[ai][bj][m][n]); __builtin_amdgcn_s_setprio(0); } while (0)
; #define G_WAIT_V(n) asm volatile("s_waitcnt vmcnt(" #n ")" ::: "memory")
; #define G_WAIT_L(n) asm volatile("s_waitcnt lgkmcnt(" #n ")" ::: "memory")
; #define G_BAR __builtin_amdgcn_s_barrier()
; #define G_SCHED __builtin_amdgcn_sched_barrier(0)
; template <class Epi>
; __device__ __forceinline__ void gemm_phase(LAS unsigned char* lds, const bf16_t* Ag, const bf16_t* Btg, const int K, const int nM, const int nN, const Epi& E) {
;     ...
;             const char* a1 = cA + (size_t)(t + 1) * kstep;
;             const char* a2 = last ? nA : cA + (size_t)(t + 2) * kstep; const char* b2 = last ? nB : cB + (size_t)(t + 2) * kstep;
;             const char* a3 = a2 + kstep; const char* b3 = b2 + kstep;
;     ...
;             G_WAIT_V(6); G_BAR; G_MMA(1, 1, At, B1); G_BAR;
;             G_LDB(B0, 1, 0); G_SCHED; G_LDA(At, 1, 0); G_STAGE(G_SA(0, 1), a2 + hstep);
;             G_WAIT_L(8); G_BAR; G_WAIT_L(0); G_MMA(0, 0, At, B0); G_BAR; G_SCHED;
;             G_LDB(B1, 1, 1); G_STAGE(G_SB(1, 0), b3);
;             G_BAR; G_WAIT_L(0); G_MMA(0, 1, At, B1); G_BAR;
;             G_LDA(At, 1, 1); G_STAGE(G_SA(1, 0), a3);
;             G_BAR; G_WAIT_L(0); G_MMA(1, 0, At, B0); G_BAR; G_SCHED;
;             G_STAGE(G_SB(1, 1), b3 + hstep);
;             G_WAIT_V(6); G_BAR; G_MMA(1, 1, At, B1); G_BAR;
	v_mfma_f32_16x16x32_bf16 v[68:71], v[236:239], v[156:159], v[68:71]
	v_mfma_f32_16x16x32_bf16 v[64:67], v[244:247], v[156:159], v[64:67]
	v_mfma_f32_16x16x32_bf16 v[52:55], v[236:239], v[164:167], v[52:55]
	v_mfma_f32_16x16x32_bf16 v[48:51], v[244:247], v[164:167], v[48:51]
	v_mfma_f32_16x16x32_bf16 v[36:39], v[236:239], v[184:187], v[36:39]
	v_mfma_f32_16x16x32_bf16 v[32:35], v[244:247], v[184:187], v[32:35]
	v_mfma_f32_16x16x32_bf16 v[20:23], v[236:239], v[228:231], v[20:23]
	v_mfma_f32_16x16x32_bf16 v[16:19], v[244:247], v[228:231], v[16:19]
	v_mfma_f32_16x16x32_bf16 v[68:71], v[240:243], v[160:163], v[68:71]
	v_mfma_f32_16x16x32_bf16 v[64:67], v[248:251], v[160:163], v[64:67]
	v_mfma_f32_16x16x32_bf16 v[52:55], v[240:243], v[180:183], v[52:55]
	v_mfma_f32_16x16x32_bf16 v[48:51], v[248:251], v[180:183], v[48:51]
	v_mfma_f32_16x16x32_bf16 v[36:39], v[240:243], v[224:227], v[36:39]
	v_mfma_f32_16x16x32_bf16 v[32:35], v[248:251], v[224:227], v[32:35]
	v_mfma_f32_16x16x32_bf16 v[20:23], v[240:243], v[232:235], v[20:23]
	v_mfma_f32_16x16x32_bf16 v[16:19], v[248:251], v[232:235], v[16:19]
	s_barrier
	ds_read_b128 v[130:133], v217 offset:32768
	ds_read_b128 v[134:137], v217 offset:33792
	ds_read_b128 v[144:147], v217 offset:34816
	ds_read_b128 v[148:151], v217 offset:35840
	s_mov_b32 m0, s62
	ds_read_b128 v[156:159], v222 offset:32768
	ds_read_b128 v[160:163], v222 offset:33792
	ds_read_b128 v[164:167], v222 offset:34816
	ds_read_b128 v[180:183], v222 offset:35840
	ds_read_b128 v[184:187], v222 offset:36864
	ds_read_b128 v[224:227], v222 offset:37888
	ds_read_b128 v[228:231], v222 offset:38912
	global_load_lds_dwordx4 v0, s[54:55]
	s_mov_b32 m0, s63
	ds_read_b128 v[232:235], v222 offset:39936
	global_load_lds_dwordx4 v2, s[54:55]
	s_waitcnt vmcnt(10) lgkmcnt(8)
	s_barrier
	s_waitcnt lgkmcnt(0)
	s_waitcnt lgkmcnt(0)
	v_mfma_f32_16x16x32_bf16 v[152:155], v[130:133], v[156:159], v[152:155]
	v_mfma_f32_16x16x32_bf16 v[138:141], v[144:147], v[156:159], v[138:141]
	v_mfma_f32_16x16x32_bf16 v[116:119], v[130:133], v[164:167], v[116:119]
	v_mfma_f32_16x16x32_bf16 v[112:115], v[144:147], v[164:167], v[112:115]
	v_mfma_f32_16x16x32_bf16 v[100:103], v[130:133], v[184:187], v[100:103]
	v_mfma_f32_16x16x32_bf16 v[96:99], v[144:147], v[184:187], v[96:99]
	v_mfma_f32_16x16x32_bf16 v[84:87], v[130:133], v[228:231], v[84:87]
	v_mfma_f32_16x16x32_bf16 v[80:83], v[144:147], v[228:231], v[80:83]
	v_mfma_f32_16x16x32_bf16 v[152:155], v[134:137], v[160:163], v[152:155]
	v_mfma_f32_16x16x32_bf16 v[140:143], v[148:151], v[160:163], v[138:141]
	v_mfma_f32_16x16x32_bf16 v[116:119], v[134:137], v[180:183], v[116:119]
	v_mfma_f32_16x16x32_bf16 v[112:115], v[148:151], v[180:183], v[112:115]
	v_mfma_f32_16x16x32_bf16 v[100:103], v[134:137], v[224:227], v[100:103]
	v_mfma_f32_16x16x32_bf16 v[96:99], v[148:151], v[224:227], v[96:99]
	v_mfma_f32_16x16x32_bf16 v[84:87], v[134:137], v[232:235], v[84:87]
	v_mfma_f32_16x16x32_bf16 v[80:83], v[148:151], v[232:235], v[80:83]
	s_barrier
	s_add_i32 m0, s59, 0x18000
	ds_read_b128 v[236:239], v217 offset:49152
	ds_read_b128 v[240:243], v217 offset:50176
	ds_read_b128 v[244:247], v217 offset:51200
	s_add_u32 s98, s52, 0x80
	s_addc_u32 s99, s53, 0
	global_load_lds_dwordx4 v0, s[98:99]
	s_add_i32 m0, s59, 0x1a000
	ds_read_b128 v[248:251], v217 offset:52224
	global_load_lds_dwordx4 v2, s[98:99]
	s_waitcnt vmcnt(10)
	s_barrier
	s_waitcnt lgkmcnt(0)
	s_waitcnt lgkmcnt(0)
	v_mfma_f32_16x16x32_bf16 v[124:127], v[236:239], v[156:159], v[124:127]
	v_mfma_f32_16x16x32_bf16 v[120:123], v[244:247], v[156:159], v[120:123]
	v_mfma_f32_16x16x32_bf16 v[108:111], v[236:239], v[164:167], v[108:111]
	v_mfma_f32_16x16x32_bf16 v[104:107], v[244:247], v[164:167], v[104:107]
	v_mfma_f32_16x16x32_bf16 v[92:95], v[236:239], v[184:187], v[92:95]
	v_mfma_f32_16x16x32_bf16 v[88:91], v[244:247], v[184:187], v[88:91]
	v_mfma_f32_16x16x32_bf16 v[76:79], v[236:239], v[228:231], v[76:79]
	v_mfma_f32_16x16x32_bf16 v[72:75], v[244:247], v[228:231], v[72:75]
	v_mfma_f32_16x16x32_bf16 v[124:127], v[240:243], v[160:163], v[124:127]
	v_mfma_f32_16x16x32_bf16 v[120:123], v[248:251], v[160:163], v[120:123]
	v_mfma_f32_16x16x32_bf16 v[108:111], v[240:243], v[180:183], v[108:111]
	v_mfma_f32_16x16x32_bf16 v[104:107], v[248:251], v[180:183], v[104:107]
	v_mfma_f32_16x16x32_bf16 v[92:95], v[240:243], v[224:227], v[92:95]
	v_mfma_f32_16x16x32_bf16 v[88:91], v[248:251], v[224:227], v[88:91]
	v_mfma_f32_16x16x32_bf16 v[76:79], v[240:243], v[232:235], v[76:79]
	v_mfma_f32_16x16x32_bf16 v[72:75], v[248:251], v[232:235], v[72:75]
	s_mov_b32 m0, s64
	s_barrier
	ds_read_b128 v[156:159], v222 offset:49152
	ds_read_b128 v[160:163], v222 offset:50176
	ds_read_b128 v[164:167], v222 offset:51200
	ds_read_b128 v[180:183], v222 offset:52224
	ds_read_b128 v[184:187], v222 offset:53248
	ds_read_b128 v[224:227], v222 offset:54272
	ds_read_b128 v[228:231], v222 offset:55296
	global_load_lds_dwordx4 v0, s[76:77]
	s_mov_b32 m0, s65
	ds_read_b128 v[232:235], v222 offset:56320
	global_load_lds_dwordx4 v2, s[76:77]
	s_barrier
	s_waitcnt lgkmcnt(0)
	s_waitcnt lgkmcnt(0)
	v_mfma_f32_16x16x32_bf16 v[60:63], v[130:133], v[156:159], v[60:63]
	v_mfma_f32_16x16x32_bf16 v[56:59], v[144:147], v[156:159], v[56:59]
	v_mfma_f32_16x16x32_bf16 v[44:47], v[130:133], v[164:167], v[44:47]
	v_mfma_f32_16x16x32_bf16 v[40:43], v[144:147], v[164:167], v[40:43]
	v_mfma_f32_16x16x32_bf16 v[28:31], v[130:133], v[184:187], v[28:31]
	v_mfma_f32_16x16x32_bf16 v[24:27], v[144:147], v[184:187], v[24:27]
	v_mfma_f32_16x16x32_bf16 v[12:15], v[130:133], v[228:231], v[12:15]
	v_mfma_f32_16x16x32_bf16 v[8:11], v[144:147], v[228:231], v[8:11]
	v_mfma_f32_16x16x32_bf16 v[60:63], v[134:137], v[160:163], v[60:63]
	v_mfma_f32_16x16x32_bf16 v[56:59], v[148:151], v[160:163], v[56:59]
	v_mfma_f32_16x16x32_bf16 v[44:47], v[134:137], v[180:183], v[44:47]
	v_mfma_f32_16x16x32_bf16 v[40:43], v[148:151], v[180:183], v[40:43]
	v_mfma_f32_16x16x32_bf16 v[28:31], v[134:137], v[224:227], v[28:31]
	v_mfma_f32_16x16x32_bf16 v[24:27], v[148:151], v[224:227], v[24:27]
	v_mfma_f32_16x16x32_bf16 v[12:15], v[134:137], v[232:235], v[12:15]
	v_mfma_f32_16x16x32_bf16 v[8:11], v[148:151], v[232:235], v[8:11]
	s_barrier
	s_add_i32 m0, s59, 0x1c000
	s_add_u32 s52, s52, 0x40080
	s_addc_u32 s53, s53, 0
	global_load_lds_dwordx4 v0, s[52:53]
	s_add_i32 m0, s59, 0x1e000
	s_add_i32 s72, s72, 2
	global_load_lds_dwordx4 v2, s[52:53]
	s_add_u32 s70, s70, 0x100
	s_addc_u32 s71, s71, 0
	s_add_u32 s50, s50, 0x100
	s_addc_u32 s51, s51, 0
	s_cmp_gt_u32 s72, 13
	s_cbranch_scc1 .LrotX_848
	s_cmp_lg_u32 s72, 12
	s_cselect_b64 s[52:53], -1, 0
	s_add_u32 s26, s50, 0xfffc0080
	s_addc_u32 s54, s51, -1
	s_and_b64 s[52:53], s[52:53], exec
	s_cselect_b32 s55, s54, s25
	s_cselect_b32 s54, s26, s24
	s_cselect_b32 s53, s71, s14
	s_cselect_b32 s52, s70, s15
; #define G_STAGE(bufoff, gbase) do { _Pragma("unroll") for (int _i = 0; _i < 2; ++_i) \
;         __builtin_amdgcn_global_load_lds((const unsigned*)((const char*)(gbase) + voff[_i]), (LAS unsigned*)(lds + (bufoff) + ldsw + _i * 8192), 16, 0, 0); } while (0)
; #define G_MMA(ai, bj, At, Bt) do { __builtin_amdgcn_s_setprio(1); _Pragma("unroll") for (int m = 0; m < 4; ++m) _Pragma("unroll") for (int n = 0; n < 2; ++n) _Pragma("unroll") for (int k = 0; k < 2; ++k) \
;         acc[ai][bj][m][n] = MFMA16(Bt[n][k], At[m][k], acc[ai][bj][m][n]); __builtin_amdgcn_s_setprio(0); } while (0)
; #define G_WAIT_V(n) asm volatile("s_waitcnt vmcnt(" #n ")" ::: "memory")
; #define G_BAR __builtin_amdgcn_s_barrier()
; template <class Epi>
; __device__ __forceinline__ void gemm_phase(LAS unsigned char* lds, const bf16_t* Ag, const bf16_t* Btg, const int K, const int nM, const int nN, const Epi& E) {
;     ...
;             G_STAGE(G_SB(1, 1), b3 + hstep);
;             G_WAIT_V(6); G_BAR; G_MMA(1, 1, At, B1); G_BAR;
;         }
.LrotX_848:
	s_waitcnt vmcnt(10)
	s_barrier
	v_mfma_f32_16x16x32_bf16 v[68:71], v[236:239], v[156:159], v[68:71]
	v_mfma_f32_16x16x32_bf16 v[64:67], v[244:247], v[156:159], v[64:67]
	v_mfma_f32_16x16x32_bf16 v[52:55], v[236:239], v[164:167], v[52:55]
	v_mfma_f32_16x16x32_bf16 v[48:51], v[244:247], v[164:167], v[48:51]
	v_mfma_f32_16x16x32_bf16 v[36:39], v[236:239], v[184:187], v[36:39]
	v_mfma_f32_16x16x32_bf16 v[32:35], v[244:247], v[184:187], v[32:35]
	v_mfma_f32_16x16x32_bf16 v[20:23], v[236:239], v[228:231], v[20:23]
	v_mfma_f32_16x16x32_bf16 v[16:19], v[244:247], v[228:231], v[16:19]
	v_mfma_f32_16x16x32_bf16 v[68:71], v[240:243], v[160:163], v[68:71]
	v_mfma_f32_16x16x32_bf16 v[64:67], v[248:251], v[160:163], v[64:67]
	v_mfma_f32_16x16x32_bf16 v[52:55], v[240:243], v[180:183], v[52:55]
	v_mfma_f32_16x16x32_bf16 v[48:51], v[248:251], v[180:183], v[48:51]
	v_mfma_f32_16x16x32_bf16 v[36:39], v[240:243], v[224:227], v[36:39]
	v_mfma_f32_16x16x32_bf16 v[32:35], v[248:251], v[224:227], v[32:35]
	v_mfma_f32_16x16x32_bf16 v[20:23], v[240:243], v[232:235], v[20:23]
	v_mfma_f32_16x16x32_bf16 v[16:19], v[248:251], v[232:235], v[16:19]
	s_cmp_gt_u32 s72, 13
	s_barrier
	s_cbranch_scc1 .LBB0_852
	s_cmp_lg_u32 s72, 12
	s_cbranch_scc1 .LmainW_848
